# removed the 16 redundant mid-segment s_setprio 0 / s_setprio 1 pairs between the two MFMA blocks of each super-phase
# speedup vs baseline: 1.0148x; 1.0086x over previous
; #define PG8_STAGE(bufoff, gbase, voff) do { _Pragma("unroll") for (int _i = 0; _i < 2; ++_i) \
;         __builtin_amdgcn_global_load_lds((const unsigned*)((const char*)(gbase) + (voff)[_i]), (PG8_LAS unsigned*)(lds + (bufoff) + ldsw + _i * 8192), 16, 0, 0); } while (0)
; #define PG8_LDA(dst, b, h) do { _Pragma("unroll") for (int m = 0; m < 4; ++m) _Pragma("unroll") for (int k = 0; k < 2; ++k) dst[m][k] = *(const PG8_LAS bf16x8*)(lds + PG8_SA(b, h) + aoff + m * 2048 + k * 1024); } while (0)
; #define PG8_LDB(dst, b, h) do { _Pragma("unroll") for (int n = 0; n < 2; ++n) _Pragma("unroll") for (int k = 0; k < 2; ++k) dst[n][k] = *(const PG8_LAS bf16x8*)(lds + PG8_SB(b, h) + boff + n * 2048 + k * 1024); } while (0)
; #define PG8_MMA(ai, bj, At, Bt) do { __builtin_amdgcn_s_setprio(1); _Pragma("unroll") for (int m = 0; m < 4; ++m) _Pragma("unroll") for (int n = 0; n < 2; ++n) _Pragma("unroll") for (int k = 0; k < 2; ++k) \
;         acc[ai][bj][m][n] = __builtin_amdgcn_mfma_f32_16x16x32_bf16(Bt[n][k], At[m][k], acc[ai][bj][m][n], 0, 0, 0); __builtin_amdgcn_s_setprio(0); } while (0)
; #define PG8_WAIT_V(n) asm volatile("s_waitcnt vmcnt(" #n ")" ::: "memory")
; #define PG8_WAIT_L(n) asm volatile("s_waitcnt lgkmcnt(" #n ")" ::: "memory")
; #define PG8_BAR __builtin_amdgcn_s_barrier()
; #define PG8_SCHED __builtin_amdgcn_sched_barrier(0)
; template <class Epi, class Sched, bool ALIGN_EPI = false, bool SP2 = false>
; __device__ __forceinline__ void gemm_phase(PG8_LAS unsigned char* lds, const Gemm g, const Sched& S, const Epi& E) {
;     ...
;             PG8_LDB(B0, 0, 0); PG8_LDB(B1, 0, 1); PG8_SCHED; PG8_LDA(At, 0, 0); PG8_STAGE(PG8_SA(1, 1), a1 + hstep, voffA);
;             PG8_WAIT_V(8); PG8_WAIT_L(0); PG8_BAR; PG8_MMA(0, 0, At, B0); PG8_MMA(0, 1, At, B1); PG8_BAR; PG8_SCHED;
;             PG8_LDA(At, 0, 1); PG8_STAGE(PG8_SB(0, 0), b2, voffB); PG8_STAGE(PG8_SB(0, 1), b2 + hstep, voffB); PG8_STAGE(PG8_SA(0, 0), a2, voffA);
.LBB0_110:
	s_add_u32 s46, s44, 0xfffc0080
	s_addc_u32 s47, s45, -1
	s_add_i32 s67, 0, 0x10000
	s_cmp_eq_u32 s66, 12
	s_cselect_b32 s49, s17, s47
	s_cselect_b32 s48, s62, s46
	v_add_u32_e32 v145, s67, v143
	s_cselect_b32 s47, s15, s65
	s_cselect_b32 s46, s63, s64
	s_add_i32 s70, 0, 0x14000
	ds_read_b128 v[146:149], v145
	ds_read_b128 v[150:153], v145 offset:1024
	ds_read_b128 v[154:157], v145 offset:2048
	ds_read_b128 v[158:161], v145 offset:3072
	v_add_u32_e32 v145, s70, v143
	ds_read_b128 v[176:179], v145
	ds_read_b128 v[180:183], v145 offset:1024
	ds_read_b128 v[184:187], v145 offset:2048
	ds_read_b128 v[188:191], v145 offset:3072
	v_lshl_add_u64 v[200:201], s[44:45], 0, v[138:139]
	s_add_i32 m0, s50, 0xc000
	ds_read_b128 v[192:195], v144
	ds_read_b128 v[196:199], v144 offset:1024
	ds_read_b128 v[208:211], v144 offset:2048
	ds_read_b128 v[212:215], v144 offset:3072
	ds_read_b128 v[216:219], v144 offset:4096
	ds_read_b128 v[220:223], v144 offset:5120
	ds_read_b128 v[224:227], v144 offset:6144
	ds_read_b128 v[228:231], v144 offset:7168
	global_load_lds_dwordx4 v[200:201], off
	v_lshl_add_u64 v[200:201], s[44:45], 0, v[140:141]
	s_add_i32 m0, s50, 0xe000
	s_nop 0
	global_load_lds_dwordx4 v[200:201], off
	s_waitcnt vmcnt(8)
	s_waitcnt lgkmcnt(0)
	s_barrier
	s_setprio 1
	s_waitcnt lgkmcnt(0)
	v_mfma_f32_16x16x32_bf16 v[126:129], v[146:149], v[192:195], v[126:129]
	v_mfma_f32_16x16x32_bf16 v[118:121], v[154:157], v[192:195], v[118:121]
	v_mfma_f32_16x16x32_bf16 v[110:113], v[146:149], v[208:211], v[110:113]
	v_mfma_f32_16x16x32_bf16 v[102:105], v[154:157], v[208:211], v[102:105]
	v_mfma_f32_16x16x32_bf16 v[94:97], v[146:149], v[216:219], v[94:97]
	v_mfma_f32_16x16x32_bf16 v[86:89], v[154:157], v[216:219], v[86:89]
	v_mfma_f32_16x16x32_bf16 v[76:79], v[146:149], v[224:227], v[76:79]
	v_mfma_f32_16x16x32_bf16 v[68:71], v[154:157], v[224:227], v[68:71]
	v_mfma_f32_16x16x32_bf16 v[126:129], v[150:153], v[196:199], v[126:129]
	v_mfma_f32_16x16x32_bf16 v[118:121], v[158:161], v[196:199], v[118:121]
	v_mfma_f32_16x16x32_bf16 v[110:113], v[150:153], v[212:215], v[110:113]
	v_mfma_f32_16x16x32_bf16 v[102:105], v[158:161], v[212:215], v[102:105]
	v_mfma_f32_16x16x32_bf16 v[94:97], v[150:153], v[220:223], v[94:97]
	v_mfma_f32_16x16x32_bf16 v[86:89], v[158:161], v[220:223], v[86:89]
	v_mfma_f32_16x16x32_bf16 v[76:79], v[150:153], v[228:231], v[76:79]
	v_mfma_f32_16x16x32_bf16 v[68:71], v[158:161], v[228:231], v[68:71]
	v_mfma_f32_16x16x32_bf16 v[122:125], v[176:179], v[192:195], v[122:125]
	v_mfma_f32_16x16x32_bf16 v[114:117], v[184:187], v[192:195], v[114:117]
	v_mfma_f32_16x16x32_bf16 v[106:109], v[176:179], v[208:211], v[106:109]
	v_mfma_f32_16x16x32_bf16 v[98:101], v[184:187], v[208:211], v[98:101]
	v_mfma_f32_16x16x32_bf16 v[90:93], v[176:179], v[216:219], v[90:93]
	v_mfma_f32_16x16x32_bf16 v[82:85], v[184:187], v[216:219], v[82:85]
	v_mfma_f32_16x16x32_bf16 v[72:75], v[176:179], v[224:227], v[72:75]
	v_mfma_f32_16x16x32_bf16 v[64:67], v[184:187], v[224:227], v[64:67]
	v_mfma_f32_16x16x32_bf16 v[122:125], v[180:183], v[196:199], v[122:125]
	v_mfma_f32_16x16x32_bf16 v[114:117], v[188:191], v[196:199], v[114:117]
	v_mfma_f32_16x16x32_bf16 v[106:109], v[180:183], v[212:215], v[106:109]
	v_mfma_f32_16x16x32_bf16 v[98:101], v[188:191], v[212:215], v[98:101]
	v_mfma_f32_16x16x32_bf16 v[90:93], v[180:183], v[220:223], v[90:93]
	v_mfma_f32_16x16x32_bf16 v[82:85], v[188:191], v[220:223], v[82:85]
	v_mfma_f32_16x16x32_bf16 v[72:75], v[180:183], v[228:231], v[72:75]
	v_mfma_f32_16x16x32_bf16 v[64:67], v[188:191], v[228:231], v[64:67]
	s_setprio 0
	s_barrier
	s_add_i32 s67, s67, s39
	v_lshl_add_u64 v[200:201], s[46:47], 0, v[134:135]
	s_mov_b32 m0, s67
	ds_read_b128 v[192:195], v144 offset:16384
	ds_read_b128 v[196:199], v144 offset:17408
	ds_read_b128 v[208:211], v144 offset:18432
	ds_read_b128 v[212:215], v144 offset:19456
	ds_read_b128 v[216:219], v144 offset:20480
	ds_read_b128 v[220:223], v144 offset:21504
	ds_read_b128 v[224:227], v144 offset:22528
	ds_read_b128 v[228:231], v144 offset:23552
	global_load_lds_dwordx4 v[200:201], off
	s_add_i32 m0, s67, 0x2000
	s_add_u32 s68, s46, 0x40000
	v_lshl_add_u64 v[232:233], s[46:47], 0, v[130:131]
	s_addc_u32 s69, s47, 0
	s_add_i32 s67, s70, s39
	global_load_lds_dwordx4 v[232:233], off
	v_lshl_add_u64 v[234:235], s[68:69], 0, v[134:135]
	s_mov_b32 m0, s67
	v_lshl_add_u64 v[236:237], s[48:49], 0, v[132:133]
	global_load_lds_dwordx4 v[234:235], off
	v_lshl_add_u64 v[234:235], s[68:69], 0, v[130:131]
	s_add_i32 m0, s67, 0x2000
	s_nop 0
	global_load_lds_dwordx4 v[234:235], off
	v_lshl_add_u64 v[234:235], s[48:49], 0, v[136:137]
	s_mov_b32 m0, s50
	s_nop 0
	global_load_lds_dwordx4 v[234:235], off
	s_mov_b32 m0, s51
	s_nop 0
	global_load_lds_dwordx4 v[236:237], off
	s_waitcnt vmcnt(8)
	s_waitcnt lgkmcnt(0)
	s_barrier
; #define PG8_STAGE(bufoff, gbase, voff) do { _Pragma("unroll") for (int _i = 0; _i < 2; ++_i) \
;         __builtin_amdgcn_global_load_lds((const unsigned*)((const char*)(gbase) + (voff)[_i]), (PG8_LAS unsigned*)(lds + (bufoff) + ldsw + _i * 8192), 16, 0, 0); } while (0)
; #define PG8_LDA(dst, b, h) do { _Pragma("unroll") for (int m = 0; m < 4; ++m) _Pragma("unroll") for (int k = 0; k < 2; ++k) dst[m][k] = *(const PG8_LAS bf16x8*)(lds + PG8_SA(b, h) + aoff + m * 2048 + k * 1024); } while (0)
; #define PG8_LDB(dst, b, h) do { _Pragma("unroll") for (int n = 0; n < 2; ++n) _Pragma("unroll") for (int k = 0; k < 2; ++k) dst[n][k] = *(const PG8_LAS bf16x8*)(lds + PG8_SB(b, h) + boff + n * 2048 + k * 1024); } while (0)
; #define PG8_MMA(ai, bj, At, Bt) do { __builtin_amdgcn_s_setprio(1); _Pragma("unroll") for (int m = 0; m < 4; ++m) _Pragma("unroll") for (int n = 0; n < 2; ++n) _Pragma("unroll") for (int k = 0; k < 2; ++k) \
;         acc[ai][bj][m][n] = __builtin_amdgcn_mfma_f32_16x16x32_bf16(Bt[n][k], At[m][k], acc[ai][bj][m][n], 0, 0, 0); __builtin_amdgcn_s_setprio(0); } while (0)
; #define PG8_WAIT_V(n) asm volatile("s_waitcnt vmcnt(" #n ")" ::: "memory")
; #define PG8_WAIT_L(n) asm volatile("s_waitcnt lgkmcnt(" #n ")" ::: "memory")
; #define PG8_BAR __builtin_amdgcn_s_barrier()
; #define PG8_SCHED __builtin_amdgcn_sched_barrier(0)
; template <class Epi, class Sched, bool ALIGN_EPI = false, bool SP2 = false>
; __device__ __forceinline__ void gemm_phase(PG8_LAS unsigned char* lds, const Gemm g, const Sched& S, const Epi& E) {
;     ...
;             PG8_WAIT_V(8); PG8_WAIT_L(0); PG8_BAR; PG8_MMA(1, 0, At, B0); PG8_MMA(1, 1, At, B1); PG8_BAR; PG8_SCHED;
;             PG8_LDB(B0, 1, 0); PG8_LDB(B1, 1, 1); PG8_SCHED; PG8_LDA(At, 1, 0); PG8_STAGE(PG8_SA(0, 1), a2 + hstep, voffA);
;             PG8_WAIT_V(8); PG8_WAIT_L(0); PG8_BAR; PG8_MMA(0, 0, At, B0); PG8_MMA(0, 1, At, B1); PG8_BAR; PG8_SCHED;
	s_setprio 1
	s_waitcnt lgkmcnt(0)
	v_mfma_f32_16x16x32_bf16 v[60:63], v[146:149], v[192:195], v[60:63]
	v_mfma_f32_16x16x32_bf16 v[52:55], v[154:157], v[192:195], v[52:55]
	v_mfma_f32_16x16x32_bf16 v[44:47], v[146:149], v[208:211], v[44:47]
	v_mfma_f32_16x16x32_bf16 v[36:39], v[154:157], v[208:211], v[36:39]
	v_mfma_f32_16x16x32_bf16 v[28:31], v[146:149], v[216:219], v[28:31]
	v_mfma_f32_16x16x32_bf16 v[20:23], v[154:157], v[216:219], v[20:23]
	v_mfma_f32_16x16x32_bf16 v[12:15], v[146:149], v[224:227], v[12:15]
	v_mfma_f32_16x16x32_bf16 v[4:7], v[154:157], v[224:227], v[4:7]
	v_mfma_f32_16x16x32_bf16 v[60:63], v[150:153], v[196:199], v[60:63]
	v_mfma_f32_16x16x32_bf16 v[52:55], v[158:161], v[196:199], v[52:55]
	v_mfma_f32_16x16x32_bf16 v[44:47], v[150:153], v[212:215], v[44:47]
	v_mfma_f32_16x16x32_bf16 v[36:39], v[158:161], v[212:215], v[36:39]
	v_mfma_f32_16x16x32_bf16 v[28:31], v[150:153], v[220:223], v[28:31]
	v_mfma_f32_16x16x32_bf16 v[20:23], v[158:161], v[220:223], v[20:23]
	v_mfma_f32_16x16x32_bf16 v[12:15], v[150:153], v[228:231], v[12:15]
	v_mfma_f32_16x16x32_bf16 v[4:7], v[158:161], v[228:231], v[4:7]
	v_mfma_f32_16x16x32_bf16 v[56:59], v[176:179], v[192:195], v[56:59]
	v_mfma_f32_16x16x32_bf16 v[48:51], v[184:187], v[192:195], v[48:51]
	v_mfma_f32_16x16x32_bf16 v[40:43], v[176:179], v[208:211], v[40:43]
	v_mfma_f32_16x16x32_bf16 v[32:35], v[184:187], v[208:211], v[32:35]
	v_mfma_f32_16x16x32_bf16 v[24:27], v[176:179], v[216:219], v[24:27]
	v_mfma_f32_16x16x32_bf16 v[16:19], v[184:187], v[216:219], v[16:19]
	v_mfma_f32_16x16x32_bf16 v[8:11], v[176:179], v[224:227], v[8:11]
	v_mfma_f32_16x16x32_bf16 v[0:3], v[184:187], v[224:227], v[0:3]
	v_mfma_f32_16x16x32_bf16 v[56:59], v[180:183], v[196:199], v[56:59]
	v_mfma_f32_16x16x32_bf16 v[48:51], v[188:191], v[196:199], v[48:51]
	v_mfma_f32_16x16x32_bf16 v[40:43], v[180:183], v[212:215], v[40:43]
	v_mfma_f32_16x16x32_bf16 v[32:35], v[188:191], v[212:215], v[32:35]
	v_mfma_f32_16x16x32_bf16 v[24:27], v[180:183], v[220:223], v[24:27]
	v_mfma_f32_16x16x32_bf16 v[16:19], v[188:191], v[220:223], v[16:19]
	v_mfma_f32_16x16x32_bf16 v[8:11], v[180:183], v[228:231], v[8:11]
	v_mfma_f32_16x16x32_bf16 v[0:3], v[188:191], v[228:231], v[0:3]
	s_setprio 0
	s_barrier
	s_add_i32 s67, 0, 0x18000
	v_add_u32_e32 v145, s67, v143
	s_add_i32 s68, 0, 0x1c000
	ds_read_b128 v[146:149], v145
	ds_read_b128 v[150:153], v145 offset:1024
	ds_read_b128 v[154:157], v145 offset:2048
	ds_read_b128 v[158:161], v145 offset:3072
	v_add_u32_e32 v145, s68, v143
	ds_read_b128 v[176:179], v145
	ds_read_b128 v[180:183], v145 offset:1024
	ds_read_b128 v[184:187], v145 offset:2048
	ds_read_b128 v[188:191], v145 offset:3072
	s_add_u32 s48, s48, 0x40000
	s_addc_u32 s49, s49, 0
	s_mov_b32 m0, s52
	v_lshl_add_u64 v[238:239], s[48:49], 0, v[136:137]
	ds_read_b128 v[192:195], v144 offset:32768
	ds_read_b128 v[196:199], v144 offset:33792
	ds_read_b128 v[208:211], v144 offset:34816
	ds_read_b128 v[212:215], v144 offset:35840
	ds_read_b128 v[216:219], v144 offset:36864
	ds_read_b128 v[220:223], v144 offset:37888
	ds_read_b128 v[224:227], v144 offset:38912
	ds_read_b128 v[228:231], v144 offset:39936
	global_load_lds_dwordx4 v[238:239], off
	v_lshl_add_u64 v[238:239], s[48:49], 0, v[132:133]
	s_mov_b32 m0, s53
	s_nop 0
	global_load_lds_dwordx4 v[238:239], off
	s_waitcnt vmcnt(8)
	s_waitcnt lgkmcnt(0)
	s_barrier
	s_setprio 1
	s_waitcnt lgkmcnt(0)
	v_mfma_f32_16x16x32_bf16 v[126:129], v[146:149], v[192:195], v[126:129]
	v_mfma_f32_16x16x32_bf16 v[118:121], v[154:157], v[192:195], v[118:121]
	v_mfma_f32_16x16x32_bf16 v[110:113], v[146:149], v[208:211], v[110:113]
	v_mfma_f32_16x16x32_bf16 v[102:105], v[154:157], v[208:211], v[102:105]
	v_mfma_f32_16x16x32_bf16 v[94:97], v[146:149], v[216:219], v[94:97]
	v_mfma_f32_16x16x32_bf16 v[86:89], v[154:157], v[216:219], v[86:89]
	v_mfma_f32_16x16x32_bf16 v[76:79], v[146:149], v[224:227], v[76:79]
	v_mfma_f32_16x16x32_bf16 v[68:71], v[154:157], v[224:227], v[68:71]
	v_mfma_f32_16x16x32_bf16 v[126:129], v[150:153], v[196:199], v[126:129]
	v_mfma_f32_16x16x32_bf16 v[118:121], v[158:161], v[196:199], v[118:121]
	v_mfma_f32_16x16x32_bf16 v[110:113], v[150:153], v[212:215], v[110:113]
	v_mfma_f32_16x16x32_bf16 v[102:105], v[158:161], v[212:215], v[102:105]
	v_mfma_f32_16x16x32_bf16 v[94:97], v[150:153], v[220:223], v[94:97]
	v_mfma_f32_16x16x32_bf16 v[86:89], v[158:161], v[220:223], v[86:89]
	v_mfma_f32_16x16x32_bf16 v[76:79], v[150:153], v[228:231], v[76:79]
	v_mfma_f32_16x16x32_bf16 v[68:71], v[158:161], v[228:231], v[68:71]
	v_mfma_f32_16x16x32_bf16 v[122:125], v[176:179], v[192:195], v[122:125]
	v_mfma_f32_16x16x32_bf16 v[114:117], v[184:187], v[192:195], v[114:117]
	v_mfma_f32_16x16x32_bf16 v[106:109], v[176:179], v[208:211], v[106:109]
	v_mfma_f32_16x16x32_bf16 v[98:101], v[184:187], v[208:211], v[98:101]
	v_mfma_f32_16x16x32_bf16 v[90:93], v[176:179], v[216:219], v[90:93]
	v_mfma_f32_16x16x32_bf16 v[82:85], v[184:187], v[216:219], v[82:85]
	v_mfma_f32_16x16x32_bf16 v[72:75], v[176:179], v[224:227], v[72:75]
	v_mfma_f32_16x16x32_bf16 v[64:67], v[184:187], v[224:227], v[64:67]
	v_mfma_f32_16x16x32_bf16 v[122:125], v[180:183], v[196:199], v[122:125]
	v_mfma_f32_16x16x32_bf16 v[114:117], v[188:191], v[196:199], v[114:117]
	v_mfma_f32_16x16x32_bf16 v[106:109], v[180:183], v[212:215], v[106:109]
	v_mfma_f32_16x16x32_bf16 v[98:101], v[188:191], v[212:215], v[98:101]
	v_mfma_f32_16x16x32_bf16 v[90:93], v[180:183], v[220:223], v[90:93]
	v_mfma_f32_16x16x32_bf16 v[82:85], v[188:191], v[220:223], v[82:85]
	v_mfma_f32_16x16x32_bf16 v[72:75], v[180:183], v[228:231], v[72:75]
	v_mfma_f32_16x16x32_bf16 v[64:67], v[188:191], v[228:231], v[64:67]
	s_setprio 0
	s_barrier
; #define PG8_STAGE(bufoff, gbase, voff) do { _Pragma("unroll") for (int _i = 0; _i < 2; ++_i) \
;         __builtin_amdgcn_global_load_lds((const unsigned*)((const char*)(gbase) + (voff)[_i]), (PG8_LAS unsigned*)(lds + (bufoff) + ldsw + _i * 8192), 16, 0, 0); } while (0)
; #define PG8_LDA(dst, b, h) do { _Pragma("unroll") for (int m = 0; m < 4; ++m) _Pragma("unroll") for (int k = 0; k < 2; ++k) dst[m][k] = *(const PG8_LAS bf16x8*)(lds + PG8_SA(b, h) + aoff + m * 2048 + k * 1024); } while (0)
; #define PG8_MMA(ai, bj, At, Bt) do { __builtin_amdgcn_s_setprio(1); _Pragma("unroll") for (int m = 0; m < 4; ++m) _Pragma("unroll") for (int n = 0; n < 2; ++n) _Pragma("unroll") for (int k = 0; k < 2; ++k) \
;         acc[ai][bj][m][n] = __builtin_amdgcn_mfma_f32_16x16x32_bf16(Bt[n][k], At[m][k], acc[ai][bj][m][n], 0, 0, 0); __builtin_amdgcn_s_setprio(0); } while (0)
; #define PG8_WAIT_V(n) asm volatile("s_waitcnt vmcnt(" #n ")" ::: "memory")
; #define PG8_WAIT_L(n) asm volatile("s_waitcnt lgkmcnt(" #n ")" ::: "memory")
; #define PG8_BAR __builtin_amdgcn_s_barrier()
; #define PG8_SCHED __builtin_amdgcn_sched_barrier(0)
; template <class Epi, class Sched, bool ALIGN_EPI = false, bool SP2 = false>
; __device__ __forceinline__ void gemm_phase(PG8_LAS unsigned char* lds, const Gemm g, const Sched& S, const Epi& E) {
;     ...
;         for (int t = 0; t < nt; t += 2) {
;             if constexpr (Epi::PF_TRIPS > 0) { if (t == nt - 2 * Epi::PF_TRIPS) E.prefetch(cur, tid, lds + STAGE_BYTES + wid * 512); }
;             const bool last = (t == nt - 2);
;             const char* a1 = cA + (size_t)(t + 1) * kstep;
;             const char* a2 = last ? nA : cA + (size_t)(t + 2) * kstep; const char* b2 = last ? nB : cB + (size_t)(t + 2) * kstep;
;             const char* a3 = a2 + kstep; const char* b3 = b2 + kstep;
;     ...
;             PG8_LDA(At, 1, 1); PG8_STAGE(PG8_SB(1, 0), b3, voffB); PG8_STAGE(PG8_SB(1, 1), b3 + hstep, voffB); PG8_STAGE(PG8_SA(1, 0), a3, voffA);
;             PG8_WAIT_V(8); PG8_WAIT_L(0); PG8_BAR; PG8_MMA(1, 0, At, B0); PG8_MMA(1, 1, At, B1); PG8_BAR; PG8_SCHED;
	s_add_i32 s48, s67, s39
	v_lshl_add_u64 v[200:201], v[200:201], 0, s[40:41]
	s_mov_b32 m0, s48
	ds_read_b128 v[192:195], v144 offset:49152
	ds_read_b128 v[196:199], v144 offset:50176
	ds_read_b128 v[208:211], v144 offset:51200
	ds_read_b128 v[212:215], v144 offset:52224
	ds_read_b128 v[216:219], v144 offset:53248
	ds_read_b128 v[220:223], v144 offset:54272
	ds_read_b128 v[224:227], v144 offset:55296
	ds_read_b128 v[228:231], v144 offset:56320
	global_load_lds_dwordx4 v[200:201], off
	s_add_i32 m0, s48, 0x2000
	s_add_u32 s46, s46, 0x40080
	v_lshl_add_u64 v[200:201], v[232:233], 0, s[40:41]
	s_addc_u32 s47, s47, 0
	s_add_i32 s48, s68, s39
	global_load_lds_dwordx4 v[200:201], off
	v_lshl_add_u64 v[200:201], s[46:47], 0, v[134:135]
	s_mov_b32 m0, s48
	s_nop 0
	global_load_lds_dwordx4 v[200:201], off
	v_lshl_add_u64 v[200:201], s[46:47], 0, v[130:131]
	s_add_i32 m0, s48, 0x2000
	s_nop 0
	global_load_lds_dwordx4 v[200:201], off
	v_lshl_add_u64 v[200:201], v[234:235], 0, s[40:41]
	s_mov_b32 m0, s56
	s_nop 0
	global_load_lds_dwordx4 v[200:201], off
	v_lshl_add_u64 v[200:201], v[236:237], 0, s[40:41]
	s_mov_b32 m0, s57
	s_nop 0
	global_load_lds_dwordx4 v[200:201], off
	s_waitcnt vmcnt(8)
	s_waitcnt lgkmcnt(0)
	s_barrier
	s_setprio 1
	s_waitcnt lgkmcnt(0)
	v_mfma_f32_16x16x32_bf16 v[60:63], v[146:149], v[192:195], v[60:63]
	v_mfma_f32_16x16x32_bf16 v[52:55], v[154:157], v[192:195], v[52:55]
	v_mfma_f32_16x16x32_bf16 v[44:47], v[146:149], v[208:211], v[44:47]
	v_mfma_f32_16x16x32_bf16 v[36:39], v[154:157], v[208:211], v[36:39]
	v_mfma_f32_16x16x32_bf16 v[28:31], v[146:149], v[216:219], v[28:31]
	v_mfma_f32_16x16x32_bf16 v[20:23], v[154:157], v[216:219], v[20:23]
	v_mfma_f32_16x16x32_bf16 v[12:15], v[146:149], v[224:227], v[12:15]
	v_mfma_f32_16x16x32_bf16 v[4:7], v[154:157], v[224:227], v[4:7]
	v_mfma_f32_16x16x32_bf16 v[60:63], v[150:153], v[196:199], v[60:63]
	v_mfma_f32_16x16x32_bf16 v[52:55], v[158:161], v[196:199], v[52:55]
	v_mfma_f32_16x16x32_bf16 v[44:47], v[150:153], v[212:215], v[44:47]
	v_mfma_f32_16x16x32_bf16 v[36:39], v[158:161], v[212:215], v[36:39]
	v_mfma_f32_16x16x32_bf16 v[28:31], v[150:153], v[220:223], v[28:31]
	v_mfma_f32_16x16x32_bf16 v[20:23], v[158:161], v[220:223], v[20:23]
	v_mfma_f32_16x16x32_bf16 v[12:15], v[150:153], v[228:231], v[12:15]
	v_mfma_f32_16x16x32_bf16 v[4:7], v[158:161], v[228:231], v[4:7]
	v_mfma_f32_16x16x32_bf16 v[56:59], v[176:179], v[192:195], v[56:59]
	v_mfma_f32_16x16x32_bf16 v[48:51], v[184:187], v[192:195], v[48:51]
	v_mfma_f32_16x16x32_bf16 v[40:43], v[176:179], v[208:211], v[40:43]
	v_mfma_f32_16x16x32_bf16 v[32:35], v[184:187], v[208:211], v[32:35]
	v_mfma_f32_16x16x32_bf16 v[24:27], v[176:179], v[216:219], v[24:27]
	v_mfma_f32_16x16x32_bf16 v[16:19], v[184:187], v[216:219], v[16:19]
	v_mfma_f32_16x16x32_bf16 v[8:11], v[176:179], v[224:227], v[8:11]
	v_mfma_f32_16x16x32_bf16 v[0:3], v[184:187], v[224:227], v[0:3]
	v_mfma_f32_16x16x32_bf16 v[56:59], v[180:183], v[196:199], v[56:59]
	v_mfma_f32_16x16x32_bf16 v[48:51], v[188:191], v[196:199], v[48:51]
	v_mfma_f32_16x16x32_bf16 v[40:43], v[180:183], v[212:215], v[40:43]
	v_mfma_f32_16x16x32_bf16 v[32:35], v[188:191], v[212:215], v[32:35]
	v_mfma_f32_16x16x32_bf16 v[24:27], v[180:183], v[220:223], v[24:27]
	v_mfma_f32_16x16x32_bf16 v[16:19], v[188:191], v[220:223], v[16:19]
	v_mfma_f32_16x16x32_bf16 v[8:11], v[180:183], v[228:231], v[8:11]
	v_mfma_f32_16x16x32_bf16 v[0:3], v[188:191], v[228:231], v[0:3]
	s_setprio 0
	s_barrier
	s_add_i32 s66, s66, 2
	s_add_u32 s44, s44, 0x100
	s_addc_u32 s45, s45, 0
	s_add_u32 s64, s64, 0x100
	s_addc_u32 s65, s65, 0
	s_cmp_gt_u32 s66, 13
	s_cbranch_scc0 .LBB0_110
	s_and_b64 vcc, exec, s[12:13]
	s_cbranch_vccz .LBB0_113
	s_barrier

; #define PG8_STAGE(bufoff, gbase, voff) do { _Pragma("unroll") for (int _i = 0; _i < 2; ++_i) \
;         __builtin_amdgcn_global_load_lds((const unsigned*)((const char*)(gbase) + (voff)[_i]), (PG8_LAS unsigned*)(lds + (bufoff) + ldsw + _i * 8192), 16, 0, 0); } while (0)
; #define PG8_LDA(dst, b, h) do { _Pragma("unroll") for (int m = 0; m < 4; ++m) _Pragma("unroll") for (int k = 0; k < 2; ++k) dst[m][k] = *(const PG8_LAS bf16x8*)(lds + PG8_SA(b, h) + aoff + m * 2048 + k * 1024); } while (0)
; #define PG8_LDB(dst, b, h) do { _Pragma("unroll") for (int n = 0; n < 2; ++n) _Pragma("unroll") for (int k = 0; k < 2; ++k) dst[n][k] = *(const PG8_LAS bf16x8*)(lds + PG8_SB(b, h) + boff + n * 2048 + k * 1024); } while (0)
; #define PG8_MMA(ai, bj, At, Bt) do { __builtin_amdgcn_s_setprio(1); _Pragma("unroll") for (int m = 0; m < 4; ++m) _Pragma("unroll") for (int n = 0; n < 2; ++n) _Pragma("unroll") for (int k = 0; k < 2; ++k) \
;         acc[ai][bj][m][n] = __builtin_amdgcn_mfma_f32_16x16x32_bf16(Bt[n][k], At[m][k], acc[ai][bj][m][n], 0, 0, 0); __builtin_amdgcn_s_setprio(0); } while (0)
; #define PG8_WAIT_V(n) asm volatile("s_waitcnt vmcnt(" #n ")" ::: "memory")
; #define PG8_WAIT_L(n) asm volatile("s_waitcnt lgkmcnt(" #n ")" ::: "memory")
; #define PG8_BAR __builtin_amdgcn_s_barrier()
; #define PG8_SCHED __builtin_amdgcn_sched_barrier(0)
; template <class Epi, class Sched, bool ALIGN_EPI = false, bool SP2 = false>
; __device__ __forceinline__ void gemm_phase(PG8_LAS unsigned char* lds, const Gemm g, const Sched& S, const Epi& E) {
;     ...
;             PG8_LDB(B0, 0, 0); PG8_LDB(B1, 0, 1); PG8_SCHED; PG8_LDA(At, 0, 0); PG8_STAGE(PG8_SA(1, 1), a1 + hstep, voffA);
;             PG8_WAIT_V(8); PG8_WAIT_L(0); PG8_BAR; PG8_MMA(0, 0, At, B0); PG8_MMA(0, 1, At, B1); PG8_BAR; PG8_SCHED;
;             PG8_LDA(At, 0, 1); PG8_STAGE(PG8_SB(0, 0), b2, voffB); PG8_STAGE(PG8_SB(0, 1), b2 + hstep, voffB); PG8_STAGE(PG8_SA(0, 0), a2, voffA);
.LBB0_129:
	s_add_u32 s48, s46, 0xfffc0080
	s_addc_u32 s49, s47, -1
	s_add_i32 s69, 0, 0x10000
	s_cmp_eq_u32 s68, 12
	s_cselect_b32 s51, s19, s49
	s_cselect_b32 s50, s64, s48
	v_add_u32_e32 v142, s69, v148
	s_cselect_b32 s49, s17, s67
	s_cselect_b32 s48, s65, s66
	s_add_i32 s72, 0, 0x14000
	ds_read_b128 v[150:153], v142
	ds_read_b128 v[154:157], v142 offset:1024
	ds_read_b128 v[158:161], v142 offset:2048
	ds_read_b128 v[176:179], v142 offset:3072
	v_add_u32_e32 v142, s72, v148
	ds_read_b128 v[180:183], v142
	ds_read_b128 v[184:187], v142 offset:1024
	ds_read_b128 v[188:191], v142 offset:2048
	ds_read_b128 v[192:195], v142 offset:3072
	v_lshl_add_u64 v[142:143], s[46:47], 0, v[138:139]
	s_add_i32 m0, s53, 0xc000
	ds_read_b128 v[196:199], v149
	ds_read_b128 v[208:211], v149 offset:1024
	ds_read_b128 v[212:215], v149 offset:2048
	ds_read_b128 v[216:219], v149 offset:3072
	ds_read_b128 v[220:223], v149 offset:4096
	ds_read_b128 v[224:227], v149 offset:5120
	ds_read_b128 v[228:231], v149 offset:6144
	ds_read_b128 v[232:235], v149 offset:7168
	global_load_lds_dwordx4 v[142:143], off
	v_lshl_add_u64 v[142:143], s[46:47], 0, v[140:141]
	s_add_i32 m0, s53, 0xe000
	s_nop 0
	global_load_lds_dwordx4 v[142:143], off
	s_waitcnt vmcnt(8)
	s_waitcnt lgkmcnt(0)
	s_barrier
	s_setprio 1
	s_waitcnt lgkmcnt(0)
	v_mfma_f32_16x16x32_bf16 v[126:129], v[150:153], v[196:199], v[126:129]
	v_mfma_f32_16x16x32_bf16 v[122:125], v[158:161], v[196:199], v[122:125]
	v_mfma_f32_16x16x32_bf16 v[114:117], v[150:153], v[212:215], v[114:117]
	v_mfma_f32_16x16x32_bf16 v[106:109], v[158:161], v[212:215], v[106:109]
	v_mfma_f32_16x16x32_bf16 v[98:101], v[150:153], v[220:223], v[98:101]
	v_mfma_f32_16x16x32_bf16 v[90:93], v[158:161], v[220:223], v[90:93]
	v_mfma_f32_16x16x32_bf16 v[82:85], v[150:153], v[228:231], v[82:85]
	v_mfma_f32_16x16x32_bf16 v[72:75], v[158:161], v[228:231], v[72:75]
	v_mfma_f32_16x16x32_bf16 v[126:129], v[154:157], v[208:211], v[126:129]
	v_mfma_f32_16x16x32_bf16 v[122:125], v[176:179], v[208:211], v[122:125]
	v_mfma_f32_16x16x32_bf16 v[114:117], v[154:157], v[216:219], v[114:117]
	v_mfma_f32_16x16x32_bf16 v[106:109], v[176:179], v[216:219], v[106:109]
	v_mfma_f32_16x16x32_bf16 v[98:101], v[154:157], v[224:227], v[98:101]
	v_mfma_f32_16x16x32_bf16 v[90:93], v[176:179], v[224:227], v[90:93]
	v_mfma_f32_16x16x32_bf16 v[82:85], v[154:157], v[232:235], v[82:85]
	v_mfma_f32_16x16x32_bf16 v[72:75], v[176:179], v[232:235], v[72:75]
	v_mfma_f32_16x16x32_bf16 v[118:121], v[180:183], v[196:199], v[118:121]
	v_mfma_f32_16x16x32_bf16 v[110:113], v[188:191], v[196:199], v[110:113]
	v_mfma_f32_16x16x32_bf16 v[102:105], v[180:183], v[212:215], v[102:105]
	v_mfma_f32_16x16x32_bf16 v[94:97], v[188:191], v[212:215], v[94:97]
	v_mfma_f32_16x16x32_bf16 v[86:89], v[180:183], v[220:223], v[86:89]
	v_mfma_f32_16x16x32_bf16 v[76:79], v[188:191], v[220:223], v[76:79]
	v_mfma_f32_16x16x32_bf16 v[68:71], v[180:183], v[228:231], v[68:71]
	v_mfma_f32_16x16x32_bf16 v[64:67], v[188:191], v[228:231], v[64:67]
	v_mfma_f32_16x16x32_bf16 v[118:121], v[184:187], v[208:211], v[118:121]
	v_mfma_f32_16x16x32_bf16 v[110:113], v[192:195], v[208:211], v[110:113]
	v_mfma_f32_16x16x32_bf16 v[102:105], v[184:187], v[216:219], v[102:105]
	v_mfma_f32_16x16x32_bf16 v[94:97], v[192:195], v[216:219], v[94:97]
	v_mfma_f32_16x16x32_bf16 v[86:89], v[184:187], v[224:227], v[86:89]
	v_mfma_f32_16x16x32_bf16 v[76:79], v[192:195], v[224:227], v[76:79]
	v_mfma_f32_16x16x32_bf16 v[68:71], v[184:187], v[232:235], v[68:71]
	v_mfma_f32_16x16x32_bf16 v[64:67], v[192:195], v[232:235], v[64:67]
	s_setprio 0
	s_barrier
	s_add_i32 s69, s69, s52
	v_lshl_add_u64 v[142:143], s[48:49], 0, v[134:135]
	s_mov_b32 m0, s69
	ds_read_b128 v[196:199], v149 offset:16384
	ds_read_b128 v[208:211], v149 offset:17408
	ds_read_b128 v[212:215], v149 offset:18432
	ds_read_b128 v[216:219], v149 offset:19456
	ds_read_b128 v[220:223], v149 offset:20480
	ds_read_b128 v[224:227], v149 offset:21504
	ds_read_b128 v[228:231], v149 offset:22528
	ds_read_b128 v[232:235], v149 offset:23552
	global_load_lds_dwordx4 v[142:143], off
	s_add_i32 m0, s69, 0x2000
	s_add_u32 s70, s48, 0x40000
	v_lshl_add_u64 v[146:147], s[48:49], 0, v[130:131]
	s_addc_u32 s71, s49, 0
	s_add_i32 s69, s72, s52
	global_load_lds_dwordx4 v[146:147], off
	v_lshl_add_u64 v[200:201], s[70:71], 0, v[134:135]
	s_mov_b32 m0, s69
	v_lshl_add_u64 v[236:237], s[50:51], 0, v[132:133]
	global_load_lds_dwordx4 v[200:201], off
	v_lshl_add_u64 v[200:201], s[70:71], 0, v[130:131]
	s_add_i32 m0, s69, 0x2000
	s_nop 0
	global_load_lds_dwordx4 v[200:201], off
	v_lshl_add_u64 v[200:201], s[50:51], 0, v[136:137]
	s_mov_b32 m0, s53
	s_nop 0
	global_load_lds_dwordx4 v[200:201], off
	s_mov_b32 m0, s54
	s_nop 0
	global_load_lds_dwordx4 v[236:237], off
	s_waitcnt vmcnt(8)
	s_waitcnt lgkmcnt(0)
	s_barrier
; #define PG8_STAGE(bufoff, gbase, voff) do { _Pragma("unroll") for (int _i = 0; _i < 2; ++_i) \
;         __builtin_amdgcn_global_load_lds((const unsigned*)((const char*)(gbase) + (voff)[_i]), (PG8_LAS unsigned*)(lds + (bufoff) + ldsw + _i * 8192), 16, 0, 0); } while (0)
; #define PG8_LDA(dst, b, h) do { _Pragma("unroll") for (int m = 0; m < 4; ++m) _Pragma("unroll") for (int k = 0; k < 2; ++k) dst[m][k] = *(const PG8_LAS bf16x8*)(lds + PG8_SA(b, h) + aoff + m * 2048 + k * 1024); } while (0)
; #define PG8_LDB(dst, b, h) do { _Pragma("unroll") for (int n = 0; n < 2; ++n) _Pragma("unroll") for (int k = 0; k < 2; ++k) dst[n][k] = *(const PG8_LAS bf16x8*)(lds + PG8_SB(b, h) + boff + n * 2048 + k * 1024); } while (0)
; #define PG8_MMA(ai, bj, At, Bt) do { __builtin_amdgcn_s_setprio(1); _Pragma("unroll") for (int m = 0; m < 4; ++m) _Pragma("unroll") for (int n = 0; n < 2; ++n) _Pragma("unroll") for (int k = 0; k < 2; ++k) \
;         acc[ai][bj][m][n] = __builtin_amdgcn_mfma_f32_16x16x32_bf16(Bt[n][k], At[m][k], acc[ai][bj][m][n], 0, 0, 0); __builtin_amdgcn_s_setprio(0); } while (0)
; #define PG8_WAIT_V(n) asm volatile("s_waitcnt vmcnt(" #n ")" ::: "memory")
; #define PG8_WAIT_L(n) asm volatile("s_waitcnt lgkmcnt(" #n ")" ::: "memory")
; #define PG8_BAR __builtin_amdgcn_s_barrier()
; #define PG8_SCHED __builtin_amdgcn_sched_barrier(0)
; template <class Epi, class Sched, bool ALIGN_EPI = false, bool SP2 = false>
; __device__ __forceinline__ void gemm_phase(PG8_LAS unsigned char* lds, const Gemm g, const Sched& S, const Epi& E) {
;     ...
;             PG8_WAIT_V(8); PG8_WAIT_L(0); PG8_BAR; PG8_MMA(1, 0, At, B0); PG8_MMA(1, 1, At, B1); PG8_BAR; PG8_SCHED;
;             PG8_LDB(B0, 1, 0); PG8_LDB(B1, 1, 1); PG8_SCHED; PG8_LDA(At, 1, 0); PG8_STAGE(PG8_SA(0, 1), a2 + hstep, voffA);
;             PG8_WAIT_V(8); PG8_WAIT_L(0); PG8_BAR; PG8_MMA(0, 0, At, B0); PG8_MMA(0, 1, At, B1); PG8_BAR; PG8_SCHED;
	s_setprio 1
	s_waitcnt lgkmcnt(0)
	v_mfma_f32_16x16x32_bf16 v[60:63], v[150:153], v[196:199], v[60:63]
	v_mfma_f32_16x16x32_bf16 v[56:59], v[158:161], v[196:199], v[56:59]
	v_mfma_f32_16x16x32_bf16 v[48:51], v[150:153], v[212:215], v[48:51]
	v_mfma_f32_16x16x32_bf16 v[40:43], v[158:161], v[212:215], v[40:43]
	v_mfma_f32_16x16x32_bf16 v[32:35], v[150:153], v[220:223], v[32:35]
	v_mfma_f32_16x16x32_bf16 v[24:27], v[158:161], v[220:223], v[24:27]
	v_mfma_f32_16x16x32_bf16 v[16:19], v[150:153], v[228:231], v[16:19]
	v_mfma_f32_16x16x32_bf16 v[8:11], v[158:161], v[228:231], v[8:11]
	v_mfma_f32_16x16x32_bf16 v[60:63], v[154:157], v[208:211], v[60:63]
	v_mfma_f32_16x16x32_bf16 v[56:59], v[176:179], v[208:211], v[56:59]
	v_mfma_f32_16x16x32_bf16 v[48:51], v[154:157], v[216:219], v[48:51]
	v_mfma_f32_16x16x32_bf16 v[40:43], v[176:179], v[216:219], v[40:43]
	v_mfma_f32_16x16x32_bf16 v[32:35], v[154:157], v[224:227], v[32:35]
	v_mfma_f32_16x16x32_bf16 v[24:27], v[176:179], v[224:227], v[24:27]
	v_mfma_f32_16x16x32_bf16 v[16:19], v[154:157], v[232:235], v[16:19]
	v_mfma_f32_16x16x32_bf16 v[8:11], v[176:179], v[232:235], v[8:11]
	v_mfma_f32_16x16x32_bf16 v[52:55], v[180:183], v[196:199], v[52:55]
	v_mfma_f32_16x16x32_bf16 v[44:47], v[188:191], v[196:199], v[44:47]
	v_mfma_f32_16x16x32_bf16 v[36:39], v[180:183], v[212:215], v[36:39]
	v_mfma_f32_16x16x32_bf16 v[28:31], v[188:191], v[212:215], v[28:31]
	v_mfma_f32_16x16x32_bf16 v[20:23], v[180:183], v[220:223], v[20:23]
	v_mfma_f32_16x16x32_bf16 v[12:15], v[188:191], v[220:223], v[12:15]
	v_mfma_f32_16x16x32_bf16 v[4:7], v[180:183], v[228:231], v[4:7]
	v_mfma_f32_16x16x32_bf16 v[0:3], v[188:191], v[228:231], v[0:3]
	v_mfma_f32_16x16x32_bf16 v[52:55], v[184:187], v[208:211], v[52:55]
	v_mfma_f32_16x16x32_bf16 v[44:47], v[192:195], v[208:211], v[44:47]
	v_mfma_f32_16x16x32_bf16 v[36:39], v[184:187], v[216:219], v[36:39]
	v_mfma_f32_16x16x32_bf16 v[28:31], v[192:195], v[216:219], v[28:31]
	v_mfma_f32_16x16x32_bf16 v[20:23], v[184:187], v[224:227], v[20:23]
	v_mfma_f32_16x16x32_bf16 v[12:15], v[192:195], v[224:227], v[12:15]
	v_mfma_f32_16x16x32_bf16 v[4:7], v[184:187], v[232:235], v[4:7]
	v_mfma_f32_16x16x32_bf16 v[0:3], v[192:195], v[232:235], v[0:3]
	s_setprio 0
	s_barrier
	s_add_i32 s69, 0, 0x18000
	v_add_u32_e32 v144, s69, v148
	s_add_i32 s70, 0, 0x1c000
	ds_read_b128 v[150:153], v144
	ds_read_b128 v[154:157], v144 offset:1024
	ds_read_b128 v[158:161], v144 offset:2048
	ds_read_b128 v[176:179], v144 offset:3072
	v_add_u32_e32 v144, s70, v148
	ds_read_b128 v[180:183], v144
	ds_read_b128 v[184:187], v144 offset:1024
	ds_read_b128 v[188:191], v144 offset:2048
	ds_read_b128 v[192:195], v144 offset:3072
	s_add_u32 s50, s50, 0x40000
	s_addc_u32 s51, s51, 0
	s_mov_b32 m0, s55
	v_lshl_add_u64 v[238:239], s[50:51], 0, v[136:137]
	ds_read_b128 v[196:199], v149 offset:32768
	ds_read_b128 v[208:211], v149 offset:33792
	ds_read_b128 v[212:215], v149 offset:34816
	ds_read_b128 v[216:219], v149 offset:35840
	ds_read_b128 v[220:223], v149 offset:36864
	ds_read_b128 v[224:227], v149 offset:37888
	ds_read_b128 v[228:231], v149 offset:38912
	ds_read_b128 v[232:235], v149 offset:39936
	global_load_lds_dwordx4 v[238:239], off
	v_lshl_add_u64 v[238:239], s[50:51], 0, v[132:133]
	s_mov_b32 m0, s56
	s_nop 0
	global_load_lds_dwordx4 v[238:239], off
	s_waitcnt vmcnt(8)
	s_waitcnt lgkmcnt(0)
	s_barrier
	s_setprio 1
	s_waitcnt lgkmcnt(0)
	v_mfma_f32_16x16x32_bf16 v[126:129], v[150:153], v[196:199], v[126:129]
	v_mfma_f32_16x16x32_bf16 v[122:125], v[158:161], v[196:199], v[122:125]
	v_mfma_f32_16x16x32_bf16 v[114:117], v[150:153], v[212:215], v[114:117]
	v_mfma_f32_16x16x32_bf16 v[106:109], v[158:161], v[212:215], v[106:109]
	v_mfma_f32_16x16x32_bf16 v[98:101], v[150:153], v[220:223], v[98:101]
	v_mfma_f32_16x16x32_bf16 v[90:93], v[158:161], v[220:223], v[90:93]
	v_mfma_f32_16x16x32_bf16 v[82:85], v[150:153], v[228:231], v[82:85]
	v_mfma_f32_16x16x32_bf16 v[72:75], v[158:161], v[228:231], v[72:75]
	v_mfma_f32_16x16x32_bf16 v[126:129], v[154:157], v[208:211], v[126:129]
	v_mfma_f32_16x16x32_bf16 v[122:125], v[176:179], v[208:211], v[122:125]
	v_mfma_f32_16x16x32_bf16 v[114:117], v[154:157], v[216:219], v[114:117]
	v_mfma_f32_16x16x32_bf16 v[106:109], v[176:179], v[216:219], v[106:109]
	v_mfma_f32_16x16x32_bf16 v[98:101], v[154:157], v[224:227], v[98:101]
	v_mfma_f32_16x16x32_bf16 v[90:93], v[176:179], v[224:227], v[90:93]
	v_mfma_f32_16x16x32_bf16 v[82:85], v[154:157], v[232:235], v[82:85]
	v_mfma_f32_16x16x32_bf16 v[72:75], v[176:179], v[232:235], v[72:75]
	v_mfma_f32_16x16x32_bf16 v[118:121], v[180:183], v[196:199], v[118:121]
	v_mfma_f32_16x16x32_bf16 v[110:113], v[188:191], v[196:199], v[110:113]
	v_mfma_f32_16x16x32_bf16 v[102:105], v[180:183], v[212:215], v[102:105]
	v_mfma_f32_16x16x32_bf16 v[94:97], v[188:191], v[212:215], v[94:97]
	v_mfma_f32_16x16x32_bf16 v[86:89], v[180:183], v[220:223], v[86:89]
	v_mfma_f32_16x16x32_bf16 v[76:79], v[188:191], v[220:223], v[76:79]
	v_mfma_f32_16x16x32_bf16 v[68:71], v[180:183], v[228:231], v[68:71]
	v_mfma_f32_16x16x32_bf16 v[64:67], v[188:191], v[228:231], v[64:67]
	v_mfma_f32_16x16x32_bf16 v[118:121], v[184:187], v[208:211], v[118:121]
	v_mfma_f32_16x16x32_bf16 v[110:113], v[192:195], v[208:211], v[110:113]
	v_mfma_f32_16x16x32_bf16 v[102:105], v[184:187], v[216:219], v[102:105]
	v_mfma_f32_16x16x32_bf16 v[94:97], v[192:195], v[216:219], v[94:97]
	v_mfma_f32_16x16x32_bf16 v[86:89], v[184:187], v[224:227], v[86:89]
	v_mfma_f32_16x16x32_bf16 v[76:79], v[192:195], v[224:227], v[76:79]
	v_mfma_f32_16x16x32_bf16 v[68:71], v[184:187], v[232:235], v[68:71]
	v_mfma_f32_16x16x32_bf16 v[64:67], v[192:195], v[232:235], v[64:67]
	s_setprio 0
	s_barrier
; #define PG8_STAGE(bufoff, gbase, voff) do { _Pragma("unroll") for (int _i = 0; _i < 2; ++_i) \
;         __builtin_amdgcn_global_load_lds((const unsigned*)((const char*)(gbase) + (voff)[_i]), (PG8_LAS unsigned*)(lds + (bufoff) + ldsw + _i * 8192), 16, 0, 0); } while (0)
; #define PG8_LDA(dst, b, h) do { _Pragma("unroll") for (int m = 0; m < 4; ++m) _Pragma("unroll") for (int k = 0; k < 2; ++k) dst[m][k] = *(const PG8_LAS bf16x8*)(lds + PG8_SA(b, h) + aoff + m * 2048 + k * 1024); } while (0)
; #define PG8_MMA(ai, bj, At, Bt) do { __builtin_amdgcn_s_setprio(1); _Pragma("unroll") for (int m = 0; m < 4; ++m) _Pragma("unroll") for (int n = 0; n < 2; ++n) _Pragma("unroll") for (int k = 0; k < 2; ++k) \
;         acc[ai][bj][m][n] = __builtin_amdgcn_mfma_f32_16x16x32_bf16(Bt[n][k], At[m][k], acc[ai][bj][m][n], 0, 0, 0); __builtin_amdgcn_s_setprio(0); } while (0)
; #define PG8_WAIT_V(n) asm volatile("s_waitcnt vmcnt(" #n ")" ::: "memory")
; #define PG8_WAIT_L(n) asm volatile("s_waitcnt lgkmcnt(" #n ")" ::: "memory")
; #define PG8_BAR __builtin_amdgcn_s_barrier()
; #define PG8_SCHED __builtin_amdgcn_sched_barrier(0)
; template <class Epi, class Sched, bool ALIGN_EPI = false, bool SP2 = false>
; __device__ __forceinline__ void gemm_phase(PG8_LAS unsigned char* lds, const Gemm g, const Sched& S, const Epi& E) {
;     ...
;         for (int t = 0; t < nt; t += 2) {
;             if constexpr (Epi::PF_TRIPS > 0) { if (t == nt - 2 * Epi::PF_TRIPS) E.prefetch(cur, tid, lds + STAGE_BYTES + wid * 512); }
;             const bool last = (t == nt - 2);
;             const char* a1 = cA + (size_t)(t + 1) * kstep;
;             const char* a2 = last ? nA : cA + (size_t)(t + 2) * kstep; const char* b2 = last ? nB : cB + (size_t)(t + 2) * kstep;
;             const char* a3 = a2 + kstep; const char* b3 = b2 + kstep;
;     ...
;             PG8_LDA(At, 1, 1); PG8_STAGE(PG8_SB(1, 0), b3, voffB); PG8_STAGE(PG8_SB(1, 1), b3 + hstep, voffB); PG8_STAGE(PG8_SA(1, 0), a3, voffA);
;             PG8_WAIT_V(8); PG8_WAIT_L(0); PG8_BAR; PG8_MMA(1, 0, At, B0); PG8_MMA(1, 1, At, B1); PG8_BAR; PG8_SCHED;
	s_add_i32 s50, s69, s52
	v_lshl_add_u64 v[142:143], v[142:143], 0, s[40:41]
	s_mov_b32 m0, s50
	ds_read_b128 v[196:199], v149 offset:49152
	ds_read_b128 v[208:211], v149 offset:50176
	ds_read_b128 v[212:215], v149 offset:51200
	ds_read_b128 v[216:219], v149 offset:52224
	ds_read_b128 v[220:223], v149 offset:53248
	ds_read_b128 v[224:227], v149 offset:54272
	ds_read_b128 v[228:231], v149 offset:55296
	ds_read_b128 v[232:235], v149 offset:56320
	global_load_lds_dwordx4 v[142:143], off
	s_add_i32 m0, s50, 0x2000
	s_add_u32 s48, s48, 0x40080
	v_lshl_add_u64 v[142:143], v[146:147], 0, s[40:41]
	s_addc_u32 s49, s49, 0
	s_add_i32 s50, s70, s52
	global_load_lds_dwordx4 v[142:143], off
	v_lshl_add_u64 v[142:143], s[48:49], 0, v[134:135]
	s_mov_b32 m0, s50
	s_nop 0
	global_load_lds_dwordx4 v[142:143], off
	v_lshl_add_u64 v[142:143], s[48:49], 0, v[130:131]
	s_add_i32 m0, s50, 0x2000
	s_nop 0
	global_load_lds_dwordx4 v[142:143], off
	v_lshl_add_u64 v[142:143], v[200:201], 0, s[40:41]
	s_mov_b32 m0, s59
	s_nop 0
	global_load_lds_dwordx4 v[142:143], off
	v_lshl_add_u64 v[142:143], v[236:237], 0, s[40:41]
	s_mov_b32 m0, s60
	s_nop 0
	global_load_lds_dwordx4 v[142:143], off
	s_waitcnt vmcnt(8)
	s_waitcnt lgkmcnt(0)
	s_barrier
	s_setprio 1
	s_waitcnt lgkmcnt(0)
	v_mfma_f32_16x16x32_bf16 v[60:63], v[150:153], v[196:199], v[60:63]
	v_mfma_f32_16x16x32_bf16 v[56:59], v[158:161], v[196:199], v[56:59]
	v_mfma_f32_16x16x32_bf16 v[48:51], v[150:153], v[212:215], v[48:51]
	v_mfma_f32_16x16x32_bf16 v[40:43], v[158:161], v[212:215], v[40:43]
	v_mfma_f32_16x16x32_bf16 v[32:35], v[150:153], v[220:223], v[32:35]
	v_mfma_f32_16x16x32_bf16 v[24:27], v[158:161], v[220:223], v[24:27]
	v_mfma_f32_16x16x32_bf16 v[16:19], v[150:153], v[228:231], v[16:19]
	v_mfma_f32_16x16x32_bf16 v[8:11], v[158:161], v[228:231], v[8:11]
	v_mfma_f32_16x16x32_bf16 v[60:63], v[154:157], v[208:211], v[60:63]
	v_mfma_f32_16x16x32_bf16 v[56:59], v[176:179], v[208:211], v[56:59]
	v_mfma_f32_16x16x32_bf16 v[48:51], v[154:157], v[216:219], v[48:51]
	v_mfma_f32_16x16x32_bf16 v[40:43], v[176:179], v[216:219], v[40:43]
	v_mfma_f32_16x16x32_bf16 v[32:35], v[154:157], v[224:227], v[32:35]
	v_mfma_f32_16x16x32_bf16 v[24:27], v[176:179], v[224:227], v[24:27]
	v_mfma_f32_16x16x32_bf16 v[16:19], v[154:157], v[232:235], v[16:19]
	v_mfma_f32_16x16x32_bf16 v[8:11], v[176:179], v[232:235], v[8:11]
	v_mfma_f32_16x16x32_bf16 v[52:55], v[180:183], v[196:199], v[52:55]
	v_mfma_f32_16x16x32_bf16 v[44:47], v[188:191], v[196:199], v[44:47]
	v_mfma_f32_16x16x32_bf16 v[36:39], v[180:183], v[212:215], v[36:39]
	v_mfma_f32_16x16x32_bf16 v[28:31], v[188:191], v[212:215], v[28:31]
	v_mfma_f32_16x16x32_bf16 v[20:23], v[180:183], v[220:223], v[20:23]
	v_mfma_f32_16x16x32_bf16 v[12:15], v[188:191], v[220:223], v[12:15]
	v_mfma_f32_16x16x32_bf16 v[4:7], v[180:183], v[228:231], v[4:7]
	v_mfma_f32_16x16x32_bf16 v[0:3], v[188:191], v[228:231], v[0:3]
	v_mfma_f32_16x16x32_bf16 v[52:55], v[184:187], v[208:211], v[52:55]
	v_mfma_f32_16x16x32_bf16 v[44:47], v[192:195], v[208:211], v[44:47]
	v_mfma_f32_16x16x32_bf16 v[36:39], v[184:187], v[216:219], v[36:39]
	v_mfma_f32_16x16x32_bf16 v[28:31], v[192:195], v[216:219], v[28:31]
	v_mfma_f32_16x16x32_bf16 v[20:23], v[184:187], v[224:227], v[20:23]
	v_mfma_f32_16x16x32_bf16 v[12:15], v[192:195], v[224:227], v[12:15]
	v_mfma_f32_16x16x32_bf16 v[4:7], v[184:187], v[232:235], v[4:7]
	v_mfma_f32_16x16x32_bf16 v[0:3], v[192:195], v[232:235], v[0:3]
	s_setprio 0
	s_barrier
	s_add_i32 s68, s68, 2
	s_add_u32 s46, s46, 0x100
	s_addc_u32 s47, s47, 0
	s_add_u32 s66, s66, 0x100
	s_addc_u32 s67, s67, 0
	s_cmp_gt_u32 s68, 13
	s_cbranch_scc0 .LBB0_129
	s_and_b64 vcc, exec, s[14:15]
	s_cbranch_vccz .LBB0_132
	s_barrier

; #define PG8_STAGE(bufoff, gbase, voff) do { _Pragma("unroll") for (int _i = 0; _i < 2; ++_i) \
;         __builtin_amdgcn_global_load_lds((const unsigned*)((const char*)(gbase) + (voff)[_i]), (PG8_LAS unsigned*)(lds + (bufoff) + ldsw + _i * 8192), 16, 0, 0); } while (0)
; #define PG8_LDA(dst, b, h) do { _Pragma("unroll") for (int m = 0; m < 4; ++m) _Pragma("unroll") for (int k = 0; k < 2; ++k) dst[m][k] = *(const PG8_LAS bf16x8*)(lds + PG8_SA(b, h) + aoff + m * 2048 + k * 1024); } while (0)
; #define PG8_LDB(dst, b, h) do { _Pragma("unroll") for (int n = 0; n < 2; ++n) _Pragma("unroll") for (int k = 0; k < 2; ++k) dst[n][k] = *(const PG8_LAS bf16x8*)(lds + PG8_SB(b, h) + boff + n * 2048 + k * 1024); } while (0)
; #define PG8_MMA(ai, bj, At, Bt) do { __builtin_amdgcn_s_setprio(1); _Pragma("unroll") for (int m = 0; m < 4; ++m) _Pragma("unroll") for (int n = 0; n < 2; ++n) _Pragma("unroll") for (int k = 0; k < 2; ++k) \
;         acc[ai][bj][m][n] = __builtin_amdgcn_mfma_f32_16x16x32_bf16(Bt[n][k], At[m][k], acc[ai][bj][m][n], 0, 0, 0); __builtin_amdgcn_s_setprio(0); } while (0)
; #define PG8_WAIT_V(n) asm volatile("s_waitcnt vmcnt(" #n ")" ::: "memory")
; #define PG8_WAIT_L(n) asm volatile("s_waitcnt lgkmcnt(" #n ")" ::: "memory")
; #define PG8_BAR __builtin_amdgcn_s_barrier()
; #define PG8_SCHED __builtin_amdgcn_sched_barrier(0)
; template <class Epi, class Sched, bool ALIGN_EPI = false, bool SP2 = false>
; __device__ __forceinline__ void gemm_phase(PG8_LAS unsigned char* lds, const Gemm g, const Sched& S, const Epi& E) {
;     ...
;             PG8_LDB(B0, 0, 0); PG8_LDB(B1, 0, 1); PG8_SCHED; PG8_LDA(At, 0, 0); PG8_STAGE(PG8_SA(1, 1), a1 + hstep, voffA);
;             PG8_WAIT_V(8); PG8_WAIT_L(0); PG8_BAR; PG8_MMA(0, 0, At, B0); PG8_MMA(0, 1, At, B1); PG8_BAR; PG8_SCHED;
;             PG8_LDA(At, 0, 1); PG8_STAGE(PG8_SB(0, 0), b2, voffB); PG8_STAGE(PG8_SB(0, 1), b2 + hstep, voffB); PG8_STAGE(PG8_SA(0, 0), a2, voffA);
.LBB0_159:
	s_add_u32 s48, s6, 0xfffc0080
	s_addc_u32 s49, s7, -1
	s_add_i32 s71, 0, 0x10000
	s_cmp_eq_u32 s70, 12
	s_cselect_b32 s51, s5, s49
	s_cselect_b32 s50, s17, s48
	s_cselect_b32 s49, s19, s69
	s_cselect_b32 s48, s67, s68
	s_add_i32 s74, 0, 0x14000
	v_add_u32_e32 v142, s71, v199
	v_add_u32_e32 v158, s74, v199
	ds_read_b128 v[130:133], v142
	ds_read_b128 v[134:137], v142 offset:1024
	ds_read_b128 v[138:141], v142 offset:2048
	s_waitcnt lgkmcnt(0)
	ds_read_b128 v[142:145], v142 offset:3072
	ds_read_b128 v[146:149], v158
	ds_read_b128 v[150:153], v158 offset:1024
	ds_read_b128 v[154:157], v158 offset:2048
	ds_read_b128 v[158:161], v158 offset:3072
	v_lshl_add_u64 v[196:197], s[6:7], 0, v[184:185]
	s_add_i32 m0, s11, 0xc000
	ds_read_b128 v[188:191], v200
	ds_read_b128 v[192:195], v200 offset:1024
	ds_read_b128 v[208:211], v200 offset:2048
	ds_read_b128 v[212:215], v200 offset:3072
	ds_read_b128 v[216:219], v200 offset:4096
	ds_read_b128 v[220:223], v200 offset:5120
	ds_read_b128 v[224:227], v200 offset:6144
	ds_read_b128 v[228:231], v200 offset:7168
	global_load_lds_dwordx4 v[196:197], off
	v_lshl_add_u64 v[196:197], s[6:7], 0, v[186:187]
	s_add_i32 m0, s11, 0xe000
	s_nop 0
	global_load_lds_dwordx4 v[196:197], off
	s_waitcnt vmcnt(8)
	s_waitcnt lgkmcnt(0)
	s_barrier
	s_setprio 1
	s_waitcnt lgkmcnt(0)
	v_mfma_f32_16x16x32_bf16 v[126:129], v[130:133], v[188:191], v[126:129]
	v_mfma_f32_16x16x32_bf16 v[122:125], v[138:141], v[188:191], v[122:125]
	v_mfma_f32_16x16x32_bf16 v[110:113], v[130:133], v[208:211], v[110:113]
	v_mfma_f32_16x16x32_bf16 v[106:109], v[138:141], v[208:211], v[106:109]
	v_mfma_f32_16x16x32_bf16 v[94:97], v[130:133], v[216:219], v[94:97]
	v_mfma_f32_16x16x32_bf16 v[90:93], v[138:141], v[216:219], v[90:93]
	v_mfma_f32_16x16x32_bf16 v[76:79], v[130:133], v[224:227], v[76:79]
	v_mfma_f32_16x16x32_bf16 v[72:75], v[138:141], v[224:227], v[72:75]
	v_mfma_f32_16x16x32_bf16 v[126:129], v[134:137], v[192:195], v[126:129]
	v_mfma_f32_16x16x32_bf16 v[122:125], v[142:145], v[192:195], v[122:125]
	v_mfma_f32_16x16x32_bf16 v[110:113], v[134:137], v[212:215], v[110:113]
	v_mfma_f32_16x16x32_bf16 v[106:109], v[142:145], v[212:215], v[106:109]
	v_mfma_f32_16x16x32_bf16 v[94:97], v[134:137], v[220:223], v[94:97]
	v_mfma_f32_16x16x32_bf16 v[90:93], v[142:145], v[220:223], v[90:93]
	v_mfma_f32_16x16x32_bf16 v[76:79], v[134:137], v[228:231], v[76:79]
	v_mfma_f32_16x16x32_bf16 v[72:75], v[142:145], v[228:231], v[72:75]
	v_mfma_f32_16x16x32_bf16 v[118:121], v[146:149], v[188:191], v[118:121]
	v_mfma_f32_16x16x32_bf16 v[114:117], v[154:157], v[188:191], v[114:117]
	v_mfma_f32_16x16x32_bf16 v[102:105], v[146:149], v[208:211], v[102:105]
	v_mfma_f32_16x16x32_bf16 v[98:101], v[154:157], v[208:211], v[98:101]
	v_mfma_f32_16x16x32_bf16 v[86:89], v[146:149], v[216:219], v[86:89]
	v_mfma_f32_16x16x32_bf16 v[82:85], v[154:157], v[216:219], v[82:85]
	v_mfma_f32_16x16x32_bf16 v[68:71], v[146:149], v[224:227], v[68:71]
	v_mfma_f32_16x16x32_bf16 v[64:67], v[154:157], v[224:227], v[64:67]
	v_mfma_f32_16x16x32_bf16 v[118:121], v[150:153], v[192:195], v[118:121]
	v_mfma_f32_16x16x32_bf16 v[114:117], v[158:161], v[192:195], v[114:117]
	v_mfma_f32_16x16x32_bf16 v[102:105], v[150:153], v[212:215], v[102:105]
	v_mfma_f32_16x16x32_bf16 v[98:101], v[158:161], v[212:215], v[98:101]
	v_mfma_f32_16x16x32_bf16 v[86:89], v[150:153], v[220:223], v[86:89]
	v_mfma_f32_16x16x32_bf16 v[82:85], v[158:161], v[220:223], v[82:85]
	v_mfma_f32_16x16x32_bf16 v[68:71], v[150:153], v[228:231], v[68:71]
	v_mfma_f32_16x16x32_bf16 v[64:67], v[158:161], v[228:231], v[64:67]
	s_setprio 0
	s_barrier
	s_add_i32 s71, s71, s54
	v_lshl_add_u64 v[196:197], s[48:49], 0, v[178:179]
	s_mov_b32 m0, s71
	ds_read_b128 v[188:191], v200 offset:16384
	ds_read_b128 v[192:195], v200 offset:17408
	ds_read_b128 v[208:211], v200 offset:18432
	ds_read_b128 v[212:215], v200 offset:19456
	ds_read_b128 v[216:219], v200 offset:20480
	ds_read_b128 v[220:223], v200 offset:21504
	ds_read_b128 v[224:227], v200 offset:22528
	ds_read_b128 v[228:231], v200 offset:23552
	global_load_lds_dwordx4 v[196:197], off
	s_add_i32 m0, s71, 0x2000
	s_add_u32 s72, s48, 0x40000
	v_lshl_add_u64 v[232:233], s[48:49], 0, v[182:183]
	s_addc_u32 s73, s49, 0
	s_add_i32 s71, s74, s54
	global_load_lds_dwordx4 v[232:233], off
	v_lshl_add_u64 v[234:235], s[72:73], 0, v[178:179]
	s_mov_b32 m0, s71
	v_lshl_add_u64 v[236:237], s[50:51], 0, v[180:181]
	global_load_lds_dwordx4 v[234:235], off
	v_lshl_add_u64 v[234:235], s[72:73], 0, v[182:183]
	s_add_i32 m0, s71, 0x2000
	s_nop 0
	global_load_lds_dwordx4 v[234:235], off
	v_lshl_add_u64 v[234:235], s[50:51], 0, v[176:177]
	s_mov_b32 m0, s11
	s_nop 0
	global_load_lds_dwordx4 v[234:235], off
	s_mov_b32 m0, s55
	s_nop 0
	global_load_lds_dwordx4 v[236:237], off
	s_waitcnt vmcnt(8)
	s_waitcnt lgkmcnt(0)
	s_barrier
; #define PG8_STAGE(bufoff, gbase, voff) do { _Pragma("unroll") for (int _i = 0; _i < 2; ++_i) \
;         __builtin_amdgcn_global_load_lds((const unsigned*)((const char*)(gbase) + (voff)[_i]), (PG8_LAS unsigned*)(lds + (bufoff) + ldsw + _i * 8192), 16, 0, 0); } while (0)
; #define PG8_LDA(dst, b, h) do { _Pragma("unroll") for (int m = 0; m < 4; ++m) _Pragma("unroll") for (int k = 0; k < 2; ++k) dst[m][k] = *(const PG8_LAS bf16x8*)(lds + PG8_SA(b, h) + aoff + m * 2048 + k * 1024); } while (0)
; #define PG8_LDB(dst, b, h) do { _Pragma("unroll") for (int n = 0; n < 2; ++n) _Pragma("unroll") for (int k = 0; k < 2; ++k) dst[n][k] = *(const PG8_LAS bf16x8*)(lds + PG8_SB(b, h) + boff + n * 2048 + k * 1024); } while (0)
; #define PG8_MMA(ai, bj, At, Bt) do { __builtin_amdgcn_s_setprio(1); _Pragma("unroll") for (int m = 0; m < 4; ++m) _Pragma("unroll") for (int n = 0; n < 2; ++n) _Pragma("unroll") for (int k = 0; k < 2; ++k) \
;         acc[ai][bj][m][n] = __builtin_amdgcn_mfma_f32_16x16x32_bf16(Bt[n][k], At[m][k], acc[ai][bj][m][n], 0, 0, 0); __builtin_amdgcn_s_setprio(0); } while (0)
; #define PG8_WAIT_V(n) asm volatile("s_waitcnt vmcnt(" #n ")" ::: "memory")
; #define PG8_WAIT_L(n) asm volatile("s_waitcnt lgkmcnt(" #n ")" ::: "memory")
; #define PG8_BAR __builtin_amdgcn_s_barrier()
; #define PG8_SCHED __builtin_amdgcn_sched_barrier(0)
; template <class Epi, class Sched, bool ALIGN_EPI = false, bool SP2 = false>
; __device__ __forceinline__ void gemm_phase(PG8_LAS unsigned char* lds, const Gemm g, const Sched& S, const Epi& E) {
;     ...
;             PG8_WAIT_V(8); PG8_WAIT_L(0); PG8_BAR; PG8_MMA(1, 0, At, B0); PG8_MMA(1, 1, At, B1); PG8_BAR; PG8_SCHED;
;             PG8_LDB(B0, 1, 0); PG8_LDB(B1, 1, 1); PG8_SCHED; PG8_LDA(At, 1, 0); PG8_STAGE(PG8_SA(0, 1), a2 + hstep, voffA);
;             PG8_WAIT_V(8); PG8_WAIT_L(0); PG8_BAR; PG8_MMA(0, 0, At, B0); PG8_MMA(0, 1, At, B1); PG8_BAR; PG8_SCHED;
	s_setprio 1
	s_waitcnt lgkmcnt(0)
	v_mfma_f32_16x16x32_bf16 v[60:63], v[130:133], v[188:191], v[60:63]
	v_mfma_f32_16x16x32_bf16 v[56:59], v[138:141], v[188:191], v[56:59]
	v_mfma_f32_16x16x32_bf16 v[44:47], v[130:133], v[208:211], v[44:47]
	v_mfma_f32_16x16x32_bf16 v[40:43], v[138:141], v[208:211], v[40:43]
	v_mfma_f32_16x16x32_bf16 v[28:31], v[130:133], v[216:219], v[28:31]
	v_mfma_f32_16x16x32_bf16 v[24:27], v[138:141], v[216:219], v[24:27]
	v_mfma_f32_16x16x32_bf16 v[12:15], v[130:133], v[224:227], v[12:15]
	v_mfma_f32_16x16x32_bf16 v[8:11], v[138:141], v[224:227], v[8:11]
	v_mfma_f32_16x16x32_bf16 v[60:63], v[134:137], v[192:195], v[60:63]
	v_mfma_f32_16x16x32_bf16 v[56:59], v[142:145], v[192:195], v[56:59]
	v_mfma_f32_16x16x32_bf16 v[44:47], v[134:137], v[212:215], v[44:47]
	v_mfma_f32_16x16x32_bf16 v[40:43], v[142:145], v[212:215], v[40:43]
	v_mfma_f32_16x16x32_bf16 v[28:31], v[134:137], v[220:223], v[28:31]
	v_mfma_f32_16x16x32_bf16 v[24:27], v[142:145], v[220:223], v[24:27]
	v_mfma_f32_16x16x32_bf16 v[12:15], v[134:137], v[228:231], v[12:15]
	v_mfma_f32_16x16x32_bf16 v[8:11], v[142:145], v[228:231], v[8:11]
	v_mfma_f32_16x16x32_bf16 v[52:55], v[146:149], v[188:191], v[52:55]
	v_mfma_f32_16x16x32_bf16 v[48:51], v[154:157], v[188:191], v[48:51]
	v_mfma_f32_16x16x32_bf16 v[36:39], v[146:149], v[208:211], v[36:39]
	v_mfma_f32_16x16x32_bf16 v[32:35], v[154:157], v[208:211], v[32:35]
	v_mfma_f32_16x16x32_bf16 v[20:23], v[146:149], v[216:219], v[20:23]
	v_mfma_f32_16x16x32_bf16 v[16:19], v[154:157], v[216:219], v[16:19]
	v_mfma_f32_16x16x32_bf16 v[4:7], v[146:149], v[224:227], v[4:7]
	v_mfma_f32_16x16x32_bf16 v[0:3], v[154:157], v[224:227], v[0:3]
	v_mfma_f32_16x16x32_bf16 v[52:55], v[150:153], v[192:195], v[52:55]
	v_mfma_f32_16x16x32_bf16 v[48:51], v[158:161], v[192:195], v[48:51]
	v_mfma_f32_16x16x32_bf16 v[36:39], v[150:153], v[212:215], v[36:39]
	v_mfma_f32_16x16x32_bf16 v[32:35], v[158:161], v[212:215], v[32:35]
	v_mfma_f32_16x16x32_bf16 v[20:23], v[150:153], v[220:223], v[20:23]
	v_mfma_f32_16x16x32_bf16 v[16:19], v[158:161], v[220:223], v[16:19]
	v_mfma_f32_16x16x32_bf16 v[4:7], v[150:153], v[228:231], v[4:7]
	v_mfma_f32_16x16x32_bf16 v[0:3], v[158:161], v[228:231], v[0:3]
	s_setprio 0
	s_barrier
	s_add_i32 s71, 0, 0x18000
	s_add_i32 s72, 0, 0x1c000
	v_add_u32_e32 v142, s71, v199
	v_add_u32_e32 v158, s72, v199
	ds_read_b128 v[130:133], v142
	ds_read_b128 v[134:137], v142 offset:1024
	ds_read_b128 v[138:141], v142 offset:2048
	ds_read_b128 v[142:145], v142 offset:3072
	ds_read_b128 v[146:149], v158
	ds_read_b128 v[150:153], v158 offset:1024
	ds_read_b128 v[154:157], v158 offset:2048
	ds_read_b128 v[158:161], v158 offset:3072
	s_add_u32 s50, s50, 0x40000
	s_addc_u32 s51, s51, 0
	s_mov_b32 m0, s56
	v_lshl_add_u64 v[238:239], s[50:51], 0, v[176:177]
	ds_read_b128 v[188:191], v200 offset:32768
	ds_read_b128 v[192:195], v200 offset:33792
	ds_read_b128 v[208:211], v200 offset:34816
	ds_read_b128 v[212:215], v200 offset:35840
	ds_read_b128 v[216:219], v200 offset:36864
	ds_read_b128 v[220:223], v200 offset:37888
	ds_read_b128 v[224:227], v200 offset:38912
	ds_read_b128 v[228:231], v200 offset:39936
	global_load_lds_dwordx4 v[238:239], off
	v_lshl_add_u64 v[238:239], s[50:51], 0, v[180:181]
	s_mov_b32 m0, s57
	s_nop 0
	global_load_lds_dwordx4 v[238:239], off
	s_waitcnt vmcnt(8)
	s_waitcnt lgkmcnt(0)
	s_barrier
	s_setprio 1
	s_waitcnt lgkmcnt(0)
	v_mfma_f32_16x16x32_bf16 v[126:129], v[130:133], v[188:191], v[126:129]
	v_mfma_f32_16x16x32_bf16 v[122:125], v[138:141], v[188:191], v[122:125]
	v_mfma_f32_16x16x32_bf16 v[110:113], v[130:133], v[208:211], v[110:113]
	v_mfma_f32_16x16x32_bf16 v[106:109], v[138:141], v[208:211], v[106:109]
	v_mfma_f32_16x16x32_bf16 v[94:97], v[130:133], v[216:219], v[94:97]
	v_mfma_f32_16x16x32_bf16 v[90:93], v[138:141], v[216:219], v[90:93]
	v_mfma_f32_16x16x32_bf16 v[76:79], v[130:133], v[224:227], v[76:79]
	v_mfma_f32_16x16x32_bf16 v[72:75], v[138:141], v[224:227], v[72:75]
	v_mfma_f32_16x16x32_bf16 v[126:129], v[134:137], v[192:195], v[126:129]
	v_mfma_f32_16x16x32_bf16 v[122:125], v[142:145], v[192:195], v[122:125]
	v_mfma_f32_16x16x32_bf16 v[110:113], v[134:137], v[212:215], v[110:113]
	v_mfma_f32_16x16x32_bf16 v[106:109], v[142:145], v[212:215], v[106:109]
	v_mfma_f32_16x16x32_bf16 v[94:97], v[134:137], v[220:223], v[94:97]
	v_mfma_f32_16x16x32_bf16 v[90:93], v[142:145], v[220:223], v[90:93]
	v_mfma_f32_16x16x32_bf16 v[76:79], v[134:137], v[228:231], v[76:79]
	v_mfma_f32_16x16x32_bf16 v[72:75], v[142:145], v[228:231], v[72:75]
	v_mfma_f32_16x16x32_bf16 v[118:121], v[146:149], v[188:191], v[118:121]
	v_mfma_f32_16x16x32_bf16 v[114:117], v[154:157], v[188:191], v[114:117]
	v_mfma_f32_16x16x32_bf16 v[102:105], v[146:149], v[208:211], v[102:105]
	v_mfma_f32_16x16x32_bf16 v[98:101], v[154:157], v[208:211], v[98:101]
	v_mfma_f32_16x16x32_bf16 v[86:89], v[146:149], v[216:219], v[86:89]
	v_mfma_f32_16x16x32_bf16 v[82:85], v[154:157], v[216:219], v[82:85]
	v_mfma_f32_16x16x32_bf16 v[68:71], v[146:149], v[224:227], v[68:71]
	v_mfma_f32_16x16x32_bf16 v[64:67], v[154:157], v[224:227], v[64:67]
	v_mfma_f32_16x16x32_bf16 v[118:121], v[150:153], v[192:195], v[118:121]
	v_mfma_f32_16x16x32_bf16 v[114:117], v[158:161], v[192:195], v[114:117]
	v_mfma_f32_16x16x32_bf16 v[102:105], v[150:153], v[212:215], v[102:105]
	v_mfma_f32_16x16x32_bf16 v[98:101], v[158:161], v[212:215], v[98:101]
	v_mfma_f32_16x16x32_bf16 v[86:89], v[150:153], v[220:223], v[86:89]
	v_mfma_f32_16x16x32_bf16 v[82:85], v[158:161], v[220:223], v[82:85]
	v_mfma_f32_16x16x32_bf16 v[68:71], v[150:153], v[228:231], v[68:71]
	v_mfma_f32_16x16x32_bf16 v[64:67], v[158:161], v[228:231], v[64:67]
	s_setprio 0
	s_barrier
; #define PG8_STAGE(bufoff, gbase, voff) do { _Pragma("unroll") for (int _i = 0; _i < 2; ++_i) \
;         __builtin_amdgcn_global_load_lds((const unsigned*)((const char*)(gbase) + (voff)[_i]), (PG8_LAS unsigned*)(lds + (bufoff) + ldsw + _i * 8192), 16, 0, 0); } while (0)
; #define PG8_LDA(dst, b, h) do { _Pragma("unroll") for (int m = 0; m < 4; ++m) _Pragma("unroll") for (int k = 0; k < 2; ++k) dst[m][k] = *(const PG8_LAS bf16x8*)(lds + PG8_SA(b, h) + aoff + m * 2048 + k * 1024); } while (0)
; #define PG8_MMA(ai, bj, At, Bt) do { __builtin_amdgcn_s_setprio(1); _Pragma("unroll") for (int m = 0; m < 4; ++m) _Pragma("unroll") for (int n = 0; n < 2; ++n) _Pragma("unroll") for (int k = 0; k < 2; ++k) \
;         acc[ai][bj][m][n] = __builtin_amdgcn_mfma_f32_16x16x32_bf16(Bt[n][k], At[m][k], acc[ai][bj][m][n], 0, 0, 0); __builtin_amdgcn_s_setprio(0); } while (0)
; #define PG8_WAIT_V(n) asm volatile("s_waitcnt vmcnt(" #n ")" ::: "memory")
; #define PG8_WAIT_L(n) asm volatile("s_waitcnt lgkmcnt(" #n ")" ::: "memory")
; #define PG8_BAR __builtin_amdgcn_s_barrier()
; #define PG8_SCHED __builtin_amdgcn_sched_barrier(0)
; template <class Epi, class Sched, bool ALIGN_EPI = false, bool SP2 = false>
; __device__ __forceinline__ void gemm_phase(PG8_LAS unsigned char* lds, const Gemm g, const Sched& S, const Epi& E) {
;     ...
;         for (int t = 0; t < nt; t += 2) {
;             if constexpr (Epi::PF_TRIPS > 0) { if (t == nt - 2 * Epi::PF_TRIPS) E.prefetch(cur, tid, lds + STAGE_BYTES + wid * 512); }
;             const bool last = (t == nt - 2);
;             const char* a1 = cA + (size_t)(t + 1) * kstep;
;             const char* a2 = last ? nA : cA + (size_t)(t + 2) * kstep; const char* b2 = last ? nB : cB + (size_t)(t + 2) * kstep;
;             const char* a3 = a2 + kstep; const char* b3 = b2 + kstep;
;     ...
;             PG8_LDA(At, 1, 1); PG8_STAGE(PG8_SB(1, 0), b3, voffB); PG8_STAGE(PG8_SB(1, 1), b3 + hstep, voffB); PG8_STAGE(PG8_SA(1, 0), a3, voffA);
;             PG8_WAIT_V(8); PG8_WAIT_L(0); PG8_BAR; PG8_MMA(1, 0, At, B0); PG8_MMA(1, 1, At, B1); PG8_BAR; PG8_SCHED;
	s_add_i32 s50, s71, s54
	v_lshl_add_u64 v[196:197], v[196:197], 0, s[40:41]
	s_mov_b32 m0, s50
	ds_read_b128 v[188:191], v200 offset:49152
	ds_read_b128 v[192:195], v200 offset:50176
	ds_read_b128 v[208:211], v200 offset:51200
	ds_read_b128 v[212:215], v200 offset:52224
	ds_read_b128 v[216:219], v200 offset:53248
	ds_read_b128 v[220:223], v200 offset:54272
	ds_read_b128 v[224:227], v200 offset:55296
	ds_read_b128 v[228:231], v200 offset:56320
	global_load_lds_dwordx4 v[196:197], off
	s_add_i32 m0, s50, 0x2000
	s_add_u32 s48, s48, 0x40080
	v_lshl_add_u64 v[196:197], v[232:233], 0, s[40:41]
	s_addc_u32 s49, s49, 0
	s_add_i32 s50, s72, s54
	global_load_lds_dwordx4 v[196:197], off
	v_lshl_add_u64 v[196:197], s[48:49], 0, v[178:179]
	s_mov_b32 m0, s50
	s_nop 0
	global_load_lds_dwordx4 v[196:197], off
	v_lshl_add_u64 v[196:197], s[48:49], 0, v[182:183]
	s_add_i32 m0, s50, 0x2000
	s_nop 0
	global_load_lds_dwordx4 v[196:197], off
	v_lshl_add_u64 v[196:197], v[234:235], 0, s[40:41]
	s_mov_b32 m0, s61
	s_nop 0
	global_load_lds_dwordx4 v[196:197], off
	v_lshl_add_u64 v[196:197], v[236:237], 0, s[40:41]
	s_mov_b32 m0, s62
	s_nop 0
	global_load_lds_dwordx4 v[196:197], off
	s_waitcnt vmcnt(8)
	s_waitcnt lgkmcnt(0)
	s_barrier
	s_setprio 1
	s_waitcnt lgkmcnt(0)
	v_mfma_f32_16x16x32_bf16 v[60:63], v[130:133], v[188:191], v[60:63]
	v_mfma_f32_16x16x32_bf16 v[56:59], v[138:141], v[188:191], v[56:59]
	v_mfma_f32_16x16x32_bf16 v[44:47], v[130:133], v[208:211], v[44:47]
	v_mfma_f32_16x16x32_bf16 v[40:43], v[138:141], v[208:211], v[40:43]
	v_mfma_f32_16x16x32_bf16 v[28:31], v[130:133], v[216:219], v[28:31]
	v_mfma_f32_16x16x32_bf16 v[24:27], v[138:141], v[216:219], v[24:27]
	v_mfma_f32_16x16x32_bf16 v[12:15], v[130:133], v[224:227], v[12:15]
	v_mfma_f32_16x16x32_bf16 v[8:11], v[138:141], v[224:227], v[8:11]
	v_mfma_f32_16x16x32_bf16 v[60:63], v[134:137], v[192:195], v[60:63]
	v_mfma_f32_16x16x32_bf16 v[56:59], v[142:145], v[192:195], v[56:59]
	v_mfma_f32_16x16x32_bf16 v[44:47], v[134:137], v[212:215], v[44:47]
	v_mfma_f32_16x16x32_bf16 v[40:43], v[142:145], v[212:215], v[40:43]
	v_mfma_f32_16x16x32_bf16 v[28:31], v[134:137], v[220:223], v[28:31]
	v_mfma_f32_16x16x32_bf16 v[24:27], v[142:145], v[220:223], v[24:27]
	v_mfma_f32_16x16x32_bf16 v[12:15], v[134:137], v[228:231], v[12:15]
	v_mfma_f32_16x16x32_bf16 v[8:11], v[142:145], v[228:231], v[8:11]
	v_mfma_f32_16x16x32_bf16 v[52:55], v[146:149], v[188:191], v[52:55]
	v_mfma_f32_16x16x32_bf16 v[48:51], v[154:157], v[188:191], v[48:51]
	v_mfma_f32_16x16x32_bf16 v[36:39], v[146:149], v[208:211], v[36:39]
	v_mfma_f32_16x16x32_bf16 v[32:35], v[154:157], v[208:211], v[32:35]
	v_mfma_f32_16x16x32_bf16 v[20:23], v[146:149], v[216:219], v[20:23]
	v_mfma_f32_16x16x32_bf16 v[16:19], v[154:157], v[216:219], v[16:19]
	v_mfma_f32_16x16x32_bf16 v[4:7], v[146:149], v[224:227], v[4:7]
	v_mfma_f32_16x16x32_bf16 v[0:3], v[154:157], v[224:227], v[0:3]
	v_mfma_f32_16x16x32_bf16 v[52:55], v[150:153], v[192:195], v[52:55]
	v_mfma_f32_16x16x32_bf16 v[48:51], v[158:161], v[192:195], v[48:51]
	v_mfma_f32_16x16x32_bf16 v[36:39], v[150:153], v[212:215], v[36:39]
	v_mfma_f32_16x16x32_bf16 v[32:35], v[158:161], v[212:215], v[32:35]
	v_mfma_f32_16x16x32_bf16 v[20:23], v[150:153], v[220:223], v[20:23]
	v_mfma_f32_16x16x32_bf16 v[16:19], v[158:161], v[220:223], v[16:19]
	v_mfma_f32_16x16x32_bf16 v[4:7], v[150:153], v[228:231], v[4:7]
	v_mfma_f32_16x16x32_bf16 v[0:3], v[158:161], v[228:231], v[0:3]
	s_setprio 0
	s_barrier
	s_add_i32 s70, s70, 2
	s_add_u32 s6, s6, 0x100
	s_addc_u32 s7, s7, 0
	s_add_u32 s68, s68, 0x100
	s_addc_u32 s69, s69, 0
	s_cmp_gt_u32 s70, 13
	s_cbranch_scc0 .LBB0_159
	s_and_b64 vcc, exec, s[14:15]
	s_cbranch_vccz .LBB0_162
	s_barrier

; #define PG8_STAGE(bufoff, gbase, voff) do { _Pragma("unroll") for (int _i = 0; _i < 2; ++_i) \
;         __builtin_amdgcn_global_load_lds((const unsigned*)((const char*)(gbase) + (voff)[_i]), (PG8_LAS unsigned*)(lds + (bufoff) + ldsw + _i * 8192), 16, 0, 0); } while (0)
; #define PG8_LDA(dst, b, h) do { _Pragma("unroll") for (int m = 0; m < 4; ++m) _Pragma("unroll") for (int k = 0; k < 2; ++k) dst[m][k] = *(const PG8_LAS bf16x8*)(lds + PG8_SA(b, h) + aoff + m * 2048 + k * 1024); } while (0)
; #define PG8_LDB(dst, b, h) do { _Pragma("unroll") for (int n = 0; n < 2; ++n) _Pragma("unroll") for (int k = 0; k < 2; ++k) dst[n][k] = *(const PG8_LAS bf16x8*)(lds + PG8_SB(b, h) + boff + n * 2048 + k * 1024); } while (0)
; #define PG8_MMA(ai, bj, At, Bt) do { __builtin_amdgcn_s_setprio(1); _Pragma("unroll") for (int m = 0; m < 4; ++m) _Pragma("unroll") for (int n = 0; n < 2; ++n) _Pragma("unroll") for (int k = 0; k < 2; ++k) \
;         acc[ai][bj][m][n] = __builtin_amdgcn_mfma_f32_16x16x32_bf16(Bt[n][k], At[m][k], acc[ai][bj][m][n], 0, 0, 0); __builtin_amdgcn_s_setprio(0); } while (0)
; #define PG8_WAIT_V(n) asm volatile("s_waitcnt vmcnt(" #n ")" ::: "memory")
; #define PG8_WAIT_L(n) asm volatile("s_waitcnt lgkmcnt(" #n ")" ::: "memory")
; #define PG8_BAR __builtin_amdgcn_s_barrier()
; #define PG8_SCHED __builtin_amdgcn_sched_barrier(0)
; template <class Epi, class Sched, bool ALIGN_EPI = false, bool SP2 = false>
; __device__ __forceinline__ void gemm_phase(PG8_LAS unsigned char* lds, const Gemm g, const Sched& S, const Epi& E) {
;     ...
;             const bool last = (t == nt - 2);
;             const char* a1 = cA + (size_t)(t + 1) * kstep;
;             const char* a2 = last ? nA : cA + (size_t)(t + 2) * kstep; const char* b2 = last ? nB : cB + (size_t)(t + 2) * kstep;
;             const char* a3 = a2 + kstep; const char* b3 = b2 + kstep;
;             if (last && has_next) S.a_ready(nxt);
;             if constexpr (SP2) {
;             PG8_LDB(B0, 0, 0); PG8_LDB(B1, 0, 1); PG8_SCHED; PG8_LDA(At, 0, 0); PG8_STAGE(PG8_SA(1, 1), a1 + hstep, voffA);
;             PG8_WAIT_V(8); PG8_WAIT_L(0); PG8_BAR; PG8_MMA(0, 0, At, B0); PG8_MMA(0, 1, At, B1); PG8_BAR; PG8_SCHED;
;             PG8_LDA(At, 0, 1); PG8_STAGE(PG8_SB(0, 0), b2, voffB); PG8_STAGE(PG8_SB(0, 1), b2 + hstep, voffB); PG8_STAGE(PG8_SA(0, 0), a2, voffA);
.LBB0_383:
	s_add_i32 s73, s56, 2
	s_add_u32 s57, s44, s54
	s_addc_u32 s74, s45, s55
	s_add_u32 s75, s57, 0x100
	s_addc_u32 s57, s74, 0
	s_add_u32 s74, s47, s54
	s_addc_u32 s76, s49, s55
	s_add_i32 s77, 0, 0x10000
	s_cmp_eq_u32 s15, s56
	s_cselect_b32 s57, s5, s57
	s_cselect_b32 s56, s4, s75
	s_cselect_b32 s75, s43, s76
	s_cselect_b32 s74, s42, s74
	s_add_i32 s76, 0, 0x14000
	v_add_u32_e32 v146, s77, v209
	v_add_u32_e32 v188, s76, v209
	ds_read_b128 v[134:137], v146
	ds_read_b128 v[138:141], v146 offset:1024
	ds_read_b128 v[142:145], v146 offset:2048
	ds_read_b128 v[146:149], v146 offset:3072
	ds_read_b128 v[150:153], v188
	ds_read_b128 v[154:157], v188 offset:1024
	ds_read_b128 v[184:187], v188 offset:2048
	ds_read_b128 v[188:191], v188 offset:3072
	v_lshl_add_u64 v[200:201], v[130:131], 0, s[54:55]
	s_add_i32 m0, s58, 0xc000
	ds_read_b128 v[192:195], v211
	ds_read_b128 v[196:199], v211 offset:1024
	ds_read_b128 v[212:215], v211 offset:2048
	ds_read_b128 v[216:219], v211 offset:3072
	ds_read_b128 v[220:223], v211 offset:4096
	ds_read_b128 v[224:227], v211 offset:5120
	ds_read_b128 v[228:231], v211 offset:6144
	ds_read_b128 v[232:235], v211 offset:7168
	global_load_lds_dwordx4 v[200:201], off
	v_lshl_add_u64 v[200:201], v[132:133], 0, s[54:55]
	s_add_i32 m0, s58, 0xe000
	s_nop 0
	global_load_lds_dwordx4 v[200:201], off
	s_waitcnt vmcnt(8)
	s_waitcnt lgkmcnt(0)
	s_barrier
	s_setprio 1
	s_waitcnt lgkmcnt(0)
	v_mfma_f32_16x16x32_bf16 v[126:129], v[134:137], v[192:195], v[126:129]
	v_mfma_f32_16x16x32_bf16 v[122:125], v[142:145], v[192:195], v[122:125]
	v_mfma_f32_16x16x32_bf16 v[110:113], v[134:137], v[212:215], v[110:113]
	v_mfma_f32_16x16x32_bf16 v[106:109], v[142:145], v[212:215], v[106:109]
	v_mfma_f32_16x16x32_bf16 v[94:97], v[134:137], v[220:223], v[94:97]
	v_mfma_f32_16x16x32_bf16 v[90:93], v[142:145], v[220:223], v[90:93]
	v_mfma_f32_16x16x32_bf16 v[76:79], v[134:137], v[228:231], v[76:79]
	v_mfma_f32_16x16x32_bf16 v[72:75], v[142:145], v[228:231], v[72:75]
	v_mfma_f32_16x16x32_bf16 v[126:129], v[138:141], v[196:199], v[126:129]
	v_mfma_f32_16x16x32_bf16 v[122:125], v[146:149], v[196:199], v[122:125]
	v_mfma_f32_16x16x32_bf16 v[110:113], v[138:141], v[216:219], v[110:113]
	v_mfma_f32_16x16x32_bf16 v[106:109], v[146:149], v[216:219], v[106:109]
	v_mfma_f32_16x16x32_bf16 v[94:97], v[138:141], v[224:227], v[94:97]
	v_mfma_f32_16x16x32_bf16 v[90:93], v[146:149], v[224:227], v[90:93]
	v_mfma_f32_16x16x32_bf16 v[76:79], v[138:141], v[232:235], v[76:79]
	v_mfma_f32_16x16x32_bf16 v[72:75], v[146:149], v[232:235], v[72:75]
	v_mfma_f32_16x16x32_bf16 v[118:121], v[150:153], v[192:195], v[118:121]
	v_mfma_f32_16x16x32_bf16 v[114:117], v[184:187], v[192:195], v[114:117]
	v_mfma_f32_16x16x32_bf16 v[102:105], v[150:153], v[212:215], v[102:105]
	v_mfma_f32_16x16x32_bf16 v[98:101], v[184:187], v[212:215], v[98:101]
	v_mfma_f32_16x16x32_bf16 v[86:89], v[150:153], v[220:223], v[86:89]
	v_mfma_f32_16x16x32_bf16 v[82:85], v[184:187], v[220:223], v[82:85]
	v_mfma_f32_16x16x32_bf16 v[68:71], v[150:153], v[228:231], v[68:71]
	v_mfma_f32_16x16x32_bf16 v[64:67], v[184:187], v[228:231], v[64:67]
	v_mfma_f32_16x16x32_bf16 v[118:121], v[154:157], v[196:199], v[118:121]
	v_mfma_f32_16x16x32_bf16 v[114:117], v[188:191], v[196:199], v[114:117]
	v_mfma_f32_16x16x32_bf16 v[102:105], v[154:157], v[216:219], v[102:105]
	v_mfma_f32_16x16x32_bf16 v[98:101], v[188:191], v[216:219], v[98:101]
	v_mfma_f32_16x16x32_bf16 v[86:89], v[154:157], v[224:227], v[86:89]
	v_mfma_f32_16x16x32_bf16 v[82:85], v[188:191], v[224:227], v[82:85]
	v_mfma_f32_16x16x32_bf16 v[68:71], v[154:157], v[232:235], v[68:71]
	v_mfma_f32_16x16x32_bf16 v[64:67], v[188:191], v[232:235], v[64:67]
	s_setprio 0
	s_barrier
	s_add_i32 s77, s77, s39
	v_lshl_add_u64 v[200:201], s[74:75], 0, v[176:177]
	s_mov_b32 m0, s77
	ds_read_b128 v[192:195], v211 offset:16384
	ds_read_b128 v[196:199], v211 offset:17408
	ds_read_b128 v[212:215], v211 offset:18432
	ds_read_b128 v[216:219], v211 offset:19456
	ds_read_b128 v[220:223], v211 offset:20480
	ds_read_b128 v[224:227], v211 offset:21504
	ds_read_b128 v[228:231], v211 offset:22528
	ds_read_b128 v[232:235], v211 offset:23552
	global_load_lds_dwordx4 v[200:201], off
	s_add_i32 m0, s77, 0x2000
	v_lshl_add_u64 v[236:237], s[74:75], 0, v[158:159]
	s_add_u32 s74, s74, s14
	s_addc_u32 s75, s75, 0
	s_add_i32 s76, s76, s39
	global_load_lds_dwordx4 v[236:237], off
	v_lshl_add_u64 v[238:239], s[74:75], 0, v[176:177]
	s_mov_b32 m0, s76
	v_lshl_add_u64 v[240:241], s[74:75], 0, v[158:159]
	global_load_lds_dwordx4 v[238:239], off
	s_add_i32 m0, s76, 0x2000
	v_lshl_add_u64 v[242:243], s[56:57], 0, v[178:179]
	global_load_lds_dwordx4 v[240:241], off
	s_mov_b32 m0, s58
	v_lshl_add_u64 v[244:245], s[56:57], 0, v[160:161]
	global_load_lds_dwordx4 v[242:243], off
	s_mov_b32 m0, s59
	s_nop 0
	global_load_lds_dwordx4 v[244:245], off
	s_waitcnt vmcnt(8)
	s_waitcnt lgkmcnt(0)
	s_barrier
; #define PG8_STAGE(bufoff, gbase, voff) do { _Pragma("unroll") for (int _i = 0; _i < 2; ++_i) \
;         __builtin_amdgcn_global_load_lds((const unsigned*)((const char*)(gbase) + (voff)[_i]), (PG8_LAS unsigned*)(lds + (bufoff) + ldsw + _i * 8192), 16, 0, 0); } while (0)
; #define PG8_LDA(dst, b, h) do { _Pragma("unroll") for (int m = 0; m < 4; ++m) _Pragma("unroll") for (int k = 0; k < 2; ++k) dst[m][k] = *(const PG8_LAS bf16x8*)(lds + PG8_SA(b, h) + aoff + m * 2048 + k * 1024); } while (0)
; #define PG8_LDB(dst, b, h) do { _Pragma("unroll") for (int n = 0; n < 2; ++n) _Pragma("unroll") for (int k = 0; k < 2; ++k) dst[n][k] = *(const PG8_LAS bf16x8*)(lds + PG8_SB(b, h) + boff + n * 2048 + k * 1024); } while (0)
; #define PG8_MMA(ai, bj, At, Bt) do { __builtin_amdgcn_s_setprio(1); _Pragma("unroll") for (int m = 0; m < 4; ++m) _Pragma("unroll") for (int n = 0; n < 2; ++n) _Pragma("unroll") for (int k = 0; k < 2; ++k) \
;         acc[ai][bj][m][n] = __builtin_amdgcn_mfma_f32_16x16x32_bf16(Bt[n][k], At[m][k], acc[ai][bj][m][n], 0, 0, 0); __builtin_amdgcn_s_setprio(0); } while (0)
; #define PG8_WAIT_V(n) asm volatile("s_waitcnt vmcnt(" #n ")" ::: "memory")
; #define PG8_WAIT_L(n) asm volatile("s_waitcnt lgkmcnt(" #n ")" ::: "memory")
; #define PG8_BAR __builtin_amdgcn_s_barrier()
; #define PG8_SCHED __builtin_amdgcn_sched_barrier(0)
; template <class Epi, class Sched, bool ALIGN_EPI = false, bool SP2 = false>
; __device__ __forceinline__ void gemm_phase(PG8_LAS unsigned char* lds, const Gemm g, const Sched& S, const Epi& E) {
;     ...
;             PG8_WAIT_V(8); PG8_WAIT_L(0); PG8_BAR; PG8_MMA(1, 0, At, B0); PG8_MMA(1, 1, At, B1); PG8_BAR; PG8_SCHED;
;             PG8_LDB(B0, 1, 0); PG8_LDB(B1, 1, 1); PG8_SCHED; PG8_LDA(At, 1, 0); PG8_STAGE(PG8_SA(0, 1), a2 + hstep, voffA);
;             PG8_WAIT_V(8); PG8_WAIT_L(0); PG8_BAR; PG8_MMA(0, 0, At, B0); PG8_MMA(0, 1, At, B1); PG8_BAR; PG8_SCHED;
	s_setprio 1
	s_waitcnt lgkmcnt(0)
	v_mfma_f32_16x16x32_bf16 v[60:63], v[134:137], v[192:195], v[60:63]
	v_mfma_f32_16x16x32_bf16 v[56:59], v[142:145], v[192:195], v[56:59]
	v_mfma_f32_16x16x32_bf16 v[44:47], v[134:137], v[212:215], v[44:47]
	v_mfma_f32_16x16x32_bf16 v[40:43], v[142:145], v[212:215], v[40:43]
	v_mfma_f32_16x16x32_bf16 v[28:31], v[134:137], v[220:223], v[28:31]
	v_mfma_f32_16x16x32_bf16 v[24:27], v[142:145], v[220:223], v[24:27]
	v_mfma_f32_16x16x32_bf16 v[12:15], v[134:137], v[228:231], v[12:15]
	v_mfma_f32_16x16x32_bf16 v[8:11], v[142:145], v[228:231], v[8:11]
	v_mfma_f32_16x16x32_bf16 v[60:63], v[138:141], v[196:199], v[60:63]
	v_mfma_f32_16x16x32_bf16 v[56:59], v[146:149], v[196:199], v[56:59]
	v_mfma_f32_16x16x32_bf16 v[44:47], v[138:141], v[216:219], v[44:47]
	v_mfma_f32_16x16x32_bf16 v[40:43], v[146:149], v[216:219], v[40:43]
	v_mfma_f32_16x16x32_bf16 v[28:31], v[138:141], v[224:227], v[28:31]
	v_mfma_f32_16x16x32_bf16 v[24:27], v[146:149], v[224:227], v[24:27]
	v_mfma_f32_16x16x32_bf16 v[12:15], v[138:141], v[232:235], v[12:15]
	v_mfma_f32_16x16x32_bf16 v[8:11], v[146:149], v[232:235], v[8:11]
	v_mfma_f32_16x16x32_bf16 v[52:55], v[150:153], v[192:195], v[52:55]
	v_mfma_f32_16x16x32_bf16 v[48:51], v[184:187], v[192:195], v[48:51]
	v_mfma_f32_16x16x32_bf16 v[36:39], v[150:153], v[212:215], v[36:39]
	v_mfma_f32_16x16x32_bf16 v[32:35], v[184:187], v[212:215], v[32:35]
	v_mfma_f32_16x16x32_bf16 v[20:23], v[150:153], v[220:223], v[20:23]
	v_mfma_f32_16x16x32_bf16 v[16:19], v[184:187], v[220:223], v[16:19]
	v_mfma_f32_16x16x32_bf16 v[4:7], v[150:153], v[228:231], v[4:7]
	v_mfma_f32_16x16x32_bf16 v[0:3], v[184:187], v[228:231], v[0:3]
	v_mfma_f32_16x16x32_bf16 v[52:55], v[154:157], v[196:199], v[52:55]
	v_mfma_f32_16x16x32_bf16 v[48:51], v[188:191], v[196:199], v[48:51]
	v_mfma_f32_16x16x32_bf16 v[36:39], v[154:157], v[216:219], v[36:39]
	v_mfma_f32_16x16x32_bf16 v[32:35], v[188:191], v[216:219], v[32:35]
	v_mfma_f32_16x16x32_bf16 v[20:23], v[154:157], v[224:227], v[20:23]
	v_mfma_f32_16x16x32_bf16 v[16:19], v[188:191], v[224:227], v[16:19]
	v_mfma_f32_16x16x32_bf16 v[4:7], v[154:157], v[232:235], v[4:7]
	v_mfma_f32_16x16x32_bf16 v[0:3], v[188:191], v[232:235], v[0:3]
	s_setprio 0
	s_barrier
	s_add_i32 s74, 0, 0x18000
	s_add_i32 s75, 0, 0x1c000
	v_add_u32_e32 v146, s74, v209
	v_add_u32_e32 v188, s75, v209
	ds_read_b128 v[134:137], v146
	ds_read_b128 v[138:141], v146 offset:1024
	ds_read_b128 v[142:145], v146 offset:2048
	ds_read_b128 v[146:149], v146 offset:3072
	ds_read_b128 v[150:153], v188
	ds_read_b128 v[154:157], v188 offset:1024
	ds_read_b128 v[184:187], v188 offset:2048
	ds_read_b128 v[188:191], v188 offset:3072
	s_add_u32 s56, s56, s14
	s_addc_u32 s57, s57, 0
	s_mov_b32 m0, s60
	v_lshl_add_u64 v[246:247], s[56:57], 0, v[178:179]
	ds_read_b128 v[192:195], v211 offset:32768
	ds_read_b128 v[196:199], v211 offset:33792
	ds_read_b128 v[212:215], v211 offset:34816
	ds_read_b128 v[216:219], v211 offset:35840
	ds_read_b128 v[220:223], v211 offset:36864
	ds_read_b128 v[224:227], v211 offset:37888
	ds_read_b128 v[228:231], v211 offset:38912
	ds_read_b128 v[232:235], v211 offset:39936
	global_load_lds_dwordx4 v[246:247], off
	v_lshl_add_u64 v[246:247], s[56:57], 0, v[160:161]
	s_mov_b32 m0, s61
	s_nop 0
	global_load_lds_dwordx4 v[246:247], off
	s_waitcnt vmcnt(8)
	s_waitcnt lgkmcnt(0)
	s_barrier
	s_setprio 1
	s_waitcnt lgkmcnt(0)
	v_mfma_f32_16x16x32_bf16 v[126:129], v[134:137], v[192:195], v[126:129]
	v_mfma_f32_16x16x32_bf16 v[122:125], v[142:145], v[192:195], v[122:125]
	v_mfma_f32_16x16x32_bf16 v[110:113], v[134:137], v[212:215], v[110:113]
	v_mfma_f32_16x16x32_bf16 v[106:109], v[142:145], v[212:215], v[106:109]
	v_mfma_f32_16x16x32_bf16 v[94:97], v[134:137], v[220:223], v[94:97]
	v_mfma_f32_16x16x32_bf16 v[90:93], v[142:145], v[220:223], v[90:93]
	v_mfma_f32_16x16x32_bf16 v[76:79], v[134:137], v[228:231], v[76:79]
	v_mfma_f32_16x16x32_bf16 v[72:75], v[142:145], v[228:231], v[72:75]
	v_mfma_f32_16x16x32_bf16 v[126:129], v[138:141], v[196:199], v[126:129]
	v_mfma_f32_16x16x32_bf16 v[122:125], v[146:149], v[196:199], v[122:125]
	v_mfma_f32_16x16x32_bf16 v[110:113], v[138:141], v[216:219], v[110:113]
	v_mfma_f32_16x16x32_bf16 v[106:109], v[146:149], v[216:219], v[106:109]
	v_mfma_f32_16x16x32_bf16 v[94:97], v[138:141], v[224:227], v[94:97]
	v_mfma_f32_16x16x32_bf16 v[90:93], v[146:149], v[224:227], v[90:93]
	v_mfma_f32_16x16x32_bf16 v[76:79], v[138:141], v[232:235], v[76:79]
	v_mfma_f32_16x16x32_bf16 v[72:75], v[146:149], v[232:235], v[72:75]
	v_mfma_f32_16x16x32_bf16 v[118:121], v[150:153], v[192:195], v[118:121]
	v_mfma_f32_16x16x32_bf16 v[114:117], v[184:187], v[192:195], v[114:117]
	v_mfma_f32_16x16x32_bf16 v[102:105], v[150:153], v[212:215], v[102:105]
	v_mfma_f32_16x16x32_bf16 v[98:101], v[184:187], v[212:215], v[98:101]
	v_mfma_f32_16x16x32_bf16 v[86:89], v[150:153], v[220:223], v[86:89]
	v_mfma_f32_16x16x32_bf16 v[82:85], v[184:187], v[220:223], v[82:85]
	v_mfma_f32_16x16x32_bf16 v[68:71], v[150:153], v[228:231], v[68:71]
	v_mfma_f32_16x16x32_bf16 v[64:67], v[184:187], v[228:231], v[64:67]
	v_mfma_f32_16x16x32_bf16 v[118:121], v[154:157], v[196:199], v[118:121]
	v_mfma_f32_16x16x32_bf16 v[114:117], v[188:191], v[196:199], v[114:117]
	v_mfma_f32_16x16x32_bf16 v[102:105], v[154:157], v[216:219], v[102:105]
	v_mfma_f32_16x16x32_bf16 v[98:101], v[188:191], v[216:219], v[98:101]
	v_mfma_f32_16x16x32_bf16 v[86:89], v[154:157], v[224:227], v[86:89]
	v_mfma_f32_16x16x32_bf16 v[82:85], v[188:191], v[224:227], v[82:85]
	v_mfma_f32_16x16x32_bf16 v[68:71], v[154:157], v[232:235], v[68:71]
	v_mfma_f32_16x16x32_bf16 v[64:67], v[188:191], v[232:235], v[64:67]
	s_setprio 0
	s_barrier
; #define PG8_STAGE(bufoff, gbase, voff) do { _Pragma("unroll") for (int _i = 0; _i < 2; ++_i) \
;         __builtin_amdgcn_global_load_lds((const unsigned*)((const char*)(gbase) + (voff)[_i]), (PG8_LAS unsigned*)(lds + (bufoff) + ldsw + _i * 8192), 16, 0, 0); } while (0)
; #define PG8_LDA(dst, b, h) do { _Pragma("unroll") for (int m = 0; m < 4; ++m) _Pragma("unroll") for (int k = 0; k < 2; ++k) dst[m][k] = *(const PG8_LAS bf16x8*)(lds + PG8_SA(b, h) + aoff + m * 2048 + k * 1024); } while (0)
; #define PG8_MMA(ai, bj, At, Bt) do { __builtin_amdgcn_s_setprio(1); _Pragma("unroll") for (int m = 0; m < 4; ++m) _Pragma("unroll") for (int n = 0; n < 2; ++n) _Pragma("unroll") for (int k = 0; k < 2; ++k) \
;         acc[ai][bj][m][n] = __builtin_amdgcn_mfma_f32_16x16x32_bf16(Bt[n][k], At[m][k], acc[ai][bj][m][n], 0, 0, 0); __builtin_amdgcn_s_setprio(0); } while (0)
; #define PG8_WAIT_V(n) asm volatile("s_waitcnt vmcnt(" #n ")" ::: "memory")
; #define PG8_WAIT_L(n) asm volatile("s_waitcnt lgkmcnt(" #n ")" ::: "memory")
; #define PG8_BAR __builtin_amdgcn_s_barrier()
; #define PG8_SCHED __builtin_amdgcn_sched_barrier(0)
; template <class Epi, class Sched, bool ALIGN_EPI = false, bool SP2 = false>
; __device__ __forceinline__ void gemm_phase(PG8_LAS unsigned char* lds, const Gemm g, const Sched& S, const Epi& E) {
;     ...
;         for (int t = 0; t < nt; t += 2) {
;             if constexpr (Epi::PF_TRIPS > 0) { if (t == nt - 2 * Epi::PF_TRIPS) E.prefetch(cur, tid, lds + STAGE_BYTES + wid * 512); }
;             const bool last = (t == nt - 2);
;             const char* a1 = cA + (size_t)(t + 1) * kstep;
;             const char* a2 = last ? nA : cA + (size_t)(t + 2) * kstep; const char* b2 = last ? nB : cB + (size_t)(t + 2) * kstep;
;             const char* a3 = a2 + kstep; const char* b3 = b2 + kstep;
;     ...
;             PG8_LDA(At, 1, 1); PG8_STAGE(PG8_SB(1, 0), b3, voffB); PG8_STAGE(PG8_SB(1, 1), b3 + hstep, voffB); PG8_STAGE(PG8_SA(1, 0), a3, voffA);
;             PG8_WAIT_V(8); PG8_WAIT_L(0); PG8_BAR; PG8_MMA(1, 0, At, B0); PG8_MMA(1, 1, At, B1); PG8_BAR; PG8_SCHED;
	s_add_i32 s56, s74, s39
	v_lshl_add_u64 v[200:201], v[200:201], 0, s[40:41]
	s_mov_b32 m0, s56
	ds_read_b128 v[192:195], v211 offset:49152
	ds_read_b128 v[196:199], v211 offset:50176
	ds_read_b128 v[212:215], v211 offset:51200
	ds_read_b128 v[216:219], v211 offset:52224
	ds_read_b128 v[220:223], v211 offset:53248
	ds_read_b128 v[224:227], v211 offset:54272
	ds_read_b128 v[228:231], v211 offset:55296
	ds_read_b128 v[232:235], v211 offset:56320
	global_load_lds_dwordx4 v[200:201], off
	v_lshl_add_u64 v[200:201], v[236:237], 0, s[40:41]
	s_add_i32 m0, s56, 0x2000
	s_add_i32 s56, s75, s39
	global_load_lds_dwordx4 v[200:201], off
	v_lshl_add_u64 v[200:201], v[238:239], 0, s[40:41]
	s_mov_b32 m0, s56
	s_nop 0
	global_load_lds_dwordx4 v[200:201], off
	v_lshl_add_u64 v[200:201], v[240:241], 0, s[40:41]
	s_add_i32 m0, s56, 0x2000
	s_nop 0
	global_load_lds_dwordx4 v[200:201], off
	v_lshl_add_u64 v[200:201], v[242:243], 0, s[40:41]
	s_mov_b32 m0, s66
	s_nop 0
	global_load_lds_dwordx4 v[200:201], off
	v_lshl_add_u64 v[200:201], v[244:245], 0, s[40:41]
	s_mov_b32 m0, s67
	s_nop 0
	global_load_lds_dwordx4 v[200:201], off
	s_waitcnt vmcnt(8)
	s_waitcnt lgkmcnt(0)
	s_barrier
	s_setprio 1
	s_waitcnt lgkmcnt(0)
	v_mfma_f32_16x16x32_bf16 v[60:63], v[134:137], v[192:195], v[60:63]
	v_mfma_f32_16x16x32_bf16 v[56:59], v[142:145], v[192:195], v[56:59]
	v_mfma_f32_16x16x32_bf16 v[44:47], v[134:137], v[212:215], v[44:47]
	v_mfma_f32_16x16x32_bf16 v[40:43], v[142:145], v[212:215], v[40:43]
	v_mfma_f32_16x16x32_bf16 v[28:31], v[134:137], v[220:223], v[28:31]
	v_mfma_f32_16x16x32_bf16 v[24:27], v[142:145], v[220:223], v[24:27]
	v_mfma_f32_16x16x32_bf16 v[12:15], v[134:137], v[228:231], v[12:15]
	v_mfma_f32_16x16x32_bf16 v[8:11], v[142:145], v[228:231], v[8:11]
	v_mfma_f32_16x16x32_bf16 v[60:63], v[138:141], v[196:199], v[60:63]
	v_mfma_f32_16x16x32_bf16 v[56:59], v[146:149], v[196:199], v[56:59]
	v_mfma_f32_16x16x32_bf16 v[44:47], v[138:141], v[216:219], v[44:47]
	v_mfma_f32_16x16x32_bf16 v[40:43], v[146:149], v[216:219], v[40:43]
	v_mfma_f32_16x16x32_bf16 v[28:31], v[138:141], v[224:227], v[28:31]
	v_mfma_f32_16x16x32_bf16 v[24:27], v[146:149], v[224:227], v[24:27]
	v_mfma_f32_16x16x32_bf16 v[12:15], v[138:141], v[232:235], v[12:15]
	v_mfma_f32_16x16x32_bf16 v[8:11], v[146:149], v[232:235], v[8:11]
	v_mfma_f32_16x16x32_bf16 v[52:55], v[150:153], v[192:195], v[52:55]
	v_mfma_f32_16x16x32_bf16 v[48:51], v[184:187], v[192:195], v[48:51]
	v_mfma_f32_16x16x32_bf16 v[36:39], v[150:153], v[212:215], v[36:39]
	v_mfma_f32_16x16x32_bf16 v[32:35], v[184:187], v[212:215], v[32:35]
	v_mfma_f32_16x16x32_bf16 v[20:23], v[150:153], v[220:223], v[20:23]
	v_mfma_f32_16x16x32_bf16 v[16:19], v[184:187], v[220:223], v[16:19]
	v_mfma_f32_16x16x32_bf16 v[4:7], v[150:153], v[228:231], v[4:7]
	v_mfma_f32_16x16x32_bf16 v[0:3], v[184:187], v[228:231], v[0:3]
	v_mfma_f32_16x16x32_bf16 v[52:55], v[154:157], v[196:199], v[52:55]
	v_mfma_f32_16x16x32_bf16 v[48:51], v[188:191], v[196:199], v[48:51]
	v_mfma_f32_16x16x32_bf16 v[36:39], v[154:157], v[216:219], v[36:39]
	v_mfma_f32_16x16x32_bf16 v[32:35], v[188:191], v[216:219], v[32:35]
	v_mfma_f32_16x16x32_bf16 v[20:23], v[154:157], v[224:227], v[20:23]
	v_mfma_f32_16x16x32_bf16 v[16:19], v[188:191], v[224:227], v[16:19]
	v_mfma_f32_16x16x32_bf16 v[4:7], v[154:157], v[232:235], v[4:7]
	v_mfma_f32_16x16x32_bf16 v[0:3], v[188:191], v[232:235], v[0:3]
	s_setprio 0
	s_barrier
	s_add_u32 s54, s54, 0x100
	s_addc_u32 s55, s55, 0
	s_cmp_ge_u32 s73, s63
	s_mov_b32 s56, s73
	s_cbranch_scc1 .LBB0_386
